# GEMM K-loops: extra s_setprio 0/1 dips after every 8 MFMAs of each 32-MFMA block
# baseline (speedup 1.0000x reference)
; #define PG8_STAGE(bufoff, gbase) do { _Pragma("unroll") for (int _i = 0; _i < 2; ++_i) \
;         __builtin_amdgcn_global_load_lds((const unsigned*)((const char*)(gbase) + voffA[_i]), (LAS unsigned*)(lds + (bufoff) + ldsw + _i * 8192), 16, 0, 0); } while (0)
; #define PG8_LDA(dst, b, h) do { _Pragma("unroll") for (int m = 0; m < 4; ++m) _Pragma("unroll") for (int k = 0; k < 2; ++k) dst[m][k] = *(const LAS bf16x8*)(lds + PG8_SA(b, h) + aoff + m * 2048 + k * 1024); } while (0)
; #define PG8_LDB(dst, b, h) do { _Pragma("unroll") for (int n = 0; n < 2; ++n) _Pragma("unroll") for (int k = 0; k < 2; ++k) dst[n][k] = *(const LAS bf16x8*)(lds + PG8_SB(b, h) + boff + n * 2048 + k * 1024); } while (0)
; #define PG8_MMA(ai, bj, At, Bt) do { __builtin_amdgcn_s_setprio(1); _Pragma("unroll") for (int m = 0; m < 4; ++m) _Pragma("unroll") for (int n = 0; n < 2; ++n) _Pragma("unroll") for (int k = 0; k < 2; ++k) \
;         acc[ai][bj][m][n] = __builtin_amdgcn_mfma_f32_16x16x32_bf16(Bt[n][k], At[m][k], acc[ai][bj][m][n], 0, 0, 0); __builtin_amdgcn_s_setprio(0); } while (0)
; #define PG8_WAIT_V(n) asm volatile("s_waitcnt vmcnt(" #n ")" ::: "memory")
; #define PG8_WAIT_L(n) asm volatile("s_waitcnt lgkmcnt(" #n ")" ::: "memory")
; #define PG8_BAR __builtin_amdgcn_s_barrier()
; #define PG8_SCHED __builtin_amdgcn_sched_barrier(0)
; template <class Epi, class Sched>
; __device__ __forceinline__ void gemm_phase(LAS unsigned char* lds, const Gemm g, const Sched& S, const Epi& E) {
;     ...
;         for (int t = 0; t < nt; t += 2) {
;             const bool last = (t == nt - 2);
;             const char* a1 = cA + (size_t)(t + 1) * kstep;
;             const char* a2 = last ? nA : cA + (size_t)(t + 2) * kstep; const char* b2 = last ? nB : cB + (size_t)(t + 2) * kstep;
;             const char* a3 = a2 + kstep; const char* b3 = b2 + kstep;
;             PG8_LDB(B0, 0, 0); PG8_LDB(B1, 0, 1); PG8_SCHED; PG8_LDA(At, 0, 0); PG8_STAGE(PG8_SA(1, 1), a1 + hstep);
;             PG8_WAIT_V(8); PG8_WAIT_L(0); PG8_BAR; PG8_MMA(0, 0, At, B0); PG8_MMA(0, 1, At, B1); PG8_BAR; PG8_SCHED;
;             PG8_LDA(At, 0, 1); PG8_STAGE(PG8_SB(0, 0), b2); PG8_STAGE(PG8_SB(0, 1), b2 + hstep); PG8_STAGE(PG8_SA(0, 0), a2);
;             PG8_WAIT_V(8); PG8_WAIT_L(0); PG8_BAR; PG8_MMA(1, 0, At, B0); PG8_MMA(1, 1, At, B1); PG8_BAR; PG8_SCHED;
.LBB0_51:
	s_add_u32 s64, s62, 0xfff80080
	s_addc_u32 s65, s63, -1
	s_add_i32 s91, 0, 0x10000
	s_cmp_eq_u32 s90, 28
	s_cselect_b32 s67, s47, s65
	s_cselect_b32 s66, s84, s64
	v_add_u32_e32 v136, s91, v139
	s_cselect_b32 s65, s45, s89
	s_cselect_b32 s64, s85, s88
	s_add_i32 s94, 0, 0x14000
	ds_read_b128 v[142:145], v136
	ds_read_b128 v[164:167], v136 offset:1024
	ds_read_b128 v[168:171], v136 offset:2048
	ds_read_b128 v[172:175], v136 offset:3072
	v_add_u32_e32 v136, s94, v139
	ds_read_b128 v[176:179], v136
	ds_read_b128 v[180:183], v136 offset:1024
	ds_read_b128 v[184:187], v136 offset:2048
	ds_read_b128 v[188:191], v136 offset:3072
	v_lshl_add_u64 v[136:137], s[62:63], 0, v[132:133]
	s_add_i32 m0, s69, 0xc000
	ds_read_b128 v[192:195], v141
	ds_read_b128 v[196:199], v141 offset:1024
	ds_read_b128 v[200:203], v141 offset:2048
	ds_read_b128 v[204:207], v141 offset:3072
	ds_read_b128 v[208:211], v141 offset:4096
	ds_read_b128 v[222:225], v141 offset:5120
	ds_read_b128 v[226:229], v141 offset:6144
	ds_read_b128 v[230:233], v141 offset:7168
	global_load_lds_dwordx4 v[136:137], off
	v_lshl_add_u64 v[136:137], s[62:63], 0, v[134:135]
	s_add_i32 m0, s69, 0xe000
	s_nop 0
	global_load_lds_dwordx4 v[136:137], off
	s_waitcnt vmcnt(8)
	s_waitcnt lgkmcnt(0)
	s_barrier
	s_setprio 1
	s_waitcnt lgkmcnt(0)
	v_mfma_f32_16x16x32_bf16 v[126:129], v[142:145], v[192:195], v[126:129]
	v_mfma_f32_16x16x32_bf16 v[118:121], v[168:171], v[192:195], v[118:121]
	v_mfma_f32_16x16x32_bf16 v[110:113], v[142:145], v[200:203], v[110:113]
	v_mfma_f32_16x16x32_bf16 v[102:105], v[168:171], v[200:203], v[102:105]
	v_mfma_f32_16x16x32_bf16 v[94:97], v[142:145], v[208:211], v[94:97]
	v_mfma_f32_16x16x32_bf16 v[86:89], v[168:171], v[208:211], v[86:89]
	v_mfma_f32_16x16x32_bf16 v[78:81], v[142:145], v[226:229], v[78:81]
	v_mfma_f32_16x16x32_bf16 v[70:73], v[168:171], v[226:229], v[70:73]
	s_setprio 0
	s_setprio 1
	v_mfma_f32_16x16x32_bf16 v[126:129], v[164:167], v[196:199], v[126:129]
	v_mfma_f32_16x16x32_bf16 v[118:121], v[172:175], v[196:199], v[118:121]
	v_mfma_f32_16x16x32_bf16 v[110:113], v[164:167], v[204:207], v[110:113]
	v_mfma_f32_16x16x32_bf16 v[102:105], v[172:175], v[204:207], v[102:105]
	v_mfma_f32_16x16x32_bf16 v[94:97], v[164:167], v[222:225], v[94:97]
	v_mfma_f32_16x16x32_bf16 v[86:89], v[172:175], v[222:225], v[86:89]
	v_mfma_f32_16x16x32_bf16 v[78:81], v[164:167], v[230:233], v[78:81]
	v_mfma_f32_16x16x32_bf16 v[70:73], v[172:175], v[230:233], v[70:73]
	s_setprio 0
	s_setprio 1
	v_mfma_f32_16x16x32_bf16 v[122:125], v[176:179], v[192:195], v[122:125]
	v_mfma_f32_16x16x32_bf16 v[114:117], v[184:187], v[192:195], v[114:117]
	v_mfma_f32_16x16x32_bf16 v[106:109], v[176:179], v[200:203], v[106:109]
	v_mfma_f32_16x16x32_bf16 v[98:101], v[184:187], v[200:203], v[98:101]
	v_mfma_f32_16x16x32_bf16 v[90:93], v[176:179], v[208:211], v[90:93]
	v_mfma_f32_16x16x32_bf16 v[82:85], v[184:187], v[208:211], v[82:85]
	v_mfma_f32_16x16x32_bf16 v[74:77], v[176:179], v[226:229], v[74:77]
	v_mfma_f32_16x16x32_bf16 v[66:69], v[184:187], v[226:229], v[66:69]
	s_setprio 0
	s_setprio 1
	v_mfma_f32_16x16x32_bf16 v[122:125], v[180:183], v[196:199], v[122:125]
	v_mfma_f32_16x16x32_bf16 v[114:117], v[188:191], v[196:199], v[114:117]
	v_mfma_f32_16x16x32_bf16 v[106:109], v[180:183], v[204:207], v[106:109]
	v_mfma_f32_16x16x32_bf16 v[98:101], v[188:191], v[204:207], v[98:101]
	v_mfma_f32_16x16x32_bf16 v[90:93], v[180:183], v[222:225], v[90:93]
	v_mfma_f32_16x16x32_bf16 v[82:85], v[188:191], v[222:225], v[82:85]
	v_mfma_f32_16x16x32_bf16 v[74:77], v[180:183], v[230:233], v[74:77]
	v_mfma_f32_16x16x32_bf16 v[66:69], v[188:191], v[230:233], v[66:69]
	s_setprio 0
	s_barrier
	s_add_i32 s91, s91, s57
	v_lshl_add_u64 v[136:137], s[64:65], 0, v[0:1]
	s_mov_b32 m0, s91
	ds_read_b128 v[192:195], v141 offset:16384
	ds_read_b128 v[196:199], v141 offset:17408
	ds_read_b128 v[200:203], v141 offset:18432
	ds_read_b128 v[204:207], v141 offset:19456
	ds_read_b128 v[208:211], v141 offset:20480
	ds_read_b128 v[222:225], v141 offset:21504
	ds_read_b128 v[226:229], v141 offset:22528
	ds_read_b128 v[230:233], v141 offset:23552
	global_load_lds_dwordx4 v[136:137], off
	s_add_i32 m0, s91, 0x2000
	s_add_u32 s92, s64, 0x80000
	v_lshl_add_u64 v[234:235], s[64:65], 0, v[130:131]
	s_addc_u32 s93, s65, 0
	s_add_i32 s91, s94, s57
	global_load_lds_dwordx4 v[234:235], off
	v_lshl_add_u64 v[236:237], s[92:93], 0, v[0:1]
	s_mov_b32 m0, s91
	v_lshl_add_u64 v[238:239], s[66:67], 0, v[130:131]
	global_load_lds_dwordx4 v[236:237], off
	v_lshl_add_u64 v[236:237], s[92:93], 0, v[130:131]
	s_add_i32 m0, s91, 0x2000
	s_nop 0
	global_load_lds_dwordx4 v[236:237], off
	v_lshl_add_u64 v[236:237], s[66:67], 0, v[0:1]
	s_mov_b32 m0, s69
	s_nop 0
	global_load_lds_dwordx4 v[236:237], off
	s_mov_b32 m0, s70
	s_nop 0
	global_load_lds_dwordx4 v[238:239], off
	s_waitcnt vmcnt(8)
	s_waitcnt lgkmcnt(0)
	s_barrier
; #define PG8_STAGE(bufoff, gbase) do { _Pragma("unroll") for (int _i = 0; _i < 2; ++_i) \
;         __builtin_amdgcn_global_load_lds((const unsigned*)((const char*)(gbase) + voffA[_i]), (LAS unsigned*)(lds + (bufoff) + ldsw + _i * 8192), 16, 0, 0); } while (0)
; #define PG8_LDA(dst, b, h) do { _Pragma("unroll") for (int m = 0; m < 4; ++m) _Pragma("unroll") for (int k = 0; k < 2; ++k) dst[m][k] = *(const LAS bf16x8*)(lds + PG8_SA(b, h) + aoff + m * 2048 + k * 1024); } while (0)
; #define PG8_LDB(dst, b, h) do { _Pragma("unroll") for (int n = 0; n < 2; ++n) _Pragma("unroll") for (int k = 0; k < 2; ++k) dst[n][k] = *(const LAS bf16x8*)(lds + PG8_SB(b, h) + boff + n * 2048 + k * 1024); } while (0)
; #define PG8_MMA(ai, bj, At, Bt) do { __builtin_amdgcn_s_setprio(1); _Pragma("unroll") for (int m = 0; m < 4; ++m) _Pragma("unroll") for (int n = 0; n < 2; ++n) _Pragma("unroll") for (int k = 0; k < 2; ++k) \
;         acc[ai][bj][m][n] = __builtin_amdgcn_mfma_f32_16x16x32_bf16(Bt[n][k], At[m][k], acc[ai][bj][m][n], 0, 0, 0); __builtin_amdgcn_s_setprio(0); } while (0)
; #define PG8_WAIT_V(n) asm volatile("s_waitcnt vmcnt(" #n ")" ::: "memory")
; #define PG8_WAIT_L(n) asm volatile("s_waitcnt lgkmcnt(" #n ")" ::: "memory")
; #define PG8_BAR __builtin_amdgcn_s_barrier()
; #define PG8_SCHED __builtin_amdgcn_sched_barrier(0)
; template <class Epi, class Sched>
; __device__ __forceinline__ void gemm_phase(LAS unsigned char* lds, const Gemm g, const Sched& S, const Epi& E) {
;     ...
;             PG8_WAIT_V(8); PG8_WAIT_L(0); PG8_BAR; PG8_MMA(1, 0, At, B0); PG8_MMA(1, 1, At, B1); PG8_BAR; PG8_SCHED;
;             PG8_LDB(B0, 1, 0); PG8_LDB(B1, 1, 1); PG8_SCHED; PG8_LDA(At, 1, 0); PG8_STAGE(PG8_SA(0, 1), a2 + hstep);
;             PG8_WAIT_V(8); PG8_WAIT_L(0); PG8_BAR; PG8_MMA(0, 0, At, B0); PG8_MMA(0, 1, At, B1); PG8_BAR; PG8_SCHED;
	s_setprio 1
	s_waitcnt lgkmcnt(0)
	v_mfma_f32_16x16x32_bf16 v[62:65], v[142:145], v[192:195], v[62:65]
	v_mfma_f32_16x16x32_bf16 v[54:57], v[168:171], v[192:195], v[54:57]
	v_mfma_f32_16x16x32_bf16 v[46:49], v[142:145], v[200:203], v[46:49]
	v_mfma_f32_16x16x32_bf16 v[38:41], v[168:171], v[200:203], v[38:41]
	v_mfma_f32_16x16x32_bf16 v[30:33], v[142:145], v[208:211], v[30:33]
	v_mfma_f32_16x16x32_bf16 v[22:25], v[168:171], v[208:211], v[22:25]
	v_mfma_f32_16x16x32_bf16 v[14:17], v[142:145], v[226:229], v[14:17]
	v_mfma_f32_16x16x32_bf16 v[6:9], v[168:171], v[226:229], v[6:9]
	s_setprio 0
	s_setprio 1
	v_mfma_f32_16x16x32_bf16 v[62:65], v[164:167], v[196:199], v[62:65]
	v_mfma_f32_16x16x32_bf16 v[54:57], v[172:175], v[196:199], v[54:57]
	v_mfma_f32_16x16x32_bf16 v[46:49], v[164:167], v[204:207], v[46:49]
	v_mfma_f32_16x16x32_bf16 v[38:41], v[172:175], v[204:207], v[38:41]
	v_mfma_f32_16x16x32_bf16 v[30:33], v[164:167], v[222:225], v[30:33]
	v_mfma_f32_16x16x32_bf16 v[22:25], v[172:175], v[222:225], v[22:25]
	v_mfma_f32_16x16x32_bf16 v[14:17], v[164:167], v[230:233], v[14:17]
	v_mfma_f32_16x16x32_bf16 v[6:9], v[172:175], v[230:233], v[6:9]
	s_setprio 0
	s_setprio 1
	v_mfma_f32_16x16x32_bf16 v[58:61], v[176:179], v[192:195], v[58:61]
	v_mfma_f32_16x16x32_bf16 v[50:53], v[184:187], v[192:195], v[50:53]
	v_mfma_f32_16x16x32_bf16 v[42:45], v[176:179], v[200:203], v[42:45]
	v_mfma_f32_16x16x32_bf16 v[34:37], v[184:187], v[200:203], v[34:37]
	v_mfma_f32_16x16x32_bf16 v[26:29], v[176:179], v[208:211], v[26:29]
	v_mfma_f32_16x16x32_bf16 v[18:21], v[184:187], v[208:211], v[18:21]
	v_mfma_f32_16x16x32_bf16 v[10:13], v[176:179], v[226:229], v[10:13]
	v_mfma_f32_16x16x32_bf16 v[2:5], v[184:187], v[226:229], v[2:5]
	s_setprio 0
	s_setprio 1
	v_mfma_f32_16x16x32_bf16 v[58:61], v[180:183], v[196:199], v[58:61]
	v_mfma_f32_16x16x32_bf16 v[50:53], v[188:191], v[196:199], v[50:53]
	v_mfma_f32_16x16x32_bf16 v[42:45], v[180:183], v[204:207], v[42:45]
	v_mfma_f32_16x16x32_bf16 v[34:37], v[188:191], v[204:207], v[34:37]
	v_mfma_f32_16x16x32_bf16 v[26:29], v[180:183], v[222:225], v[26:29]
	v_mfma_f32_16x16x32_bf16 v[18:21], v[188:191], v[222:225], v[18:21]
	v_mfma_f32_16x16x32_bf16 v[10:13], v[180:183], v[230:233], v[10:13]
	v_mfma_f32_16x16x32_bf16 v[2:5], v[188:191], v[230:233], v[2:5]
	s_setprio 0
	s_barrier
	s_add_i32 s91, 0, 0x1c000
	v_add_u32_e32 v172, s99, v139
	v_add_u32_e32 v188, s91, v139
	ds_read_b128 v[142:145], v172
	ds_read_b128 v[164:167], v172 offset:1024
	ds_read_b128 v[168:171], v172 offset:2048
	ds_read_b128 v[172:175], v172 offset:3072
	ds_read_b128 v[176:179], v188
	ds_read_b128 v[180:183], v188 offset:1024
	ds_read_b128 v[184:187], v188 offset:2048
	ds_read_b128 v[188:191], v188 offset:3072
	s_add_u32 s66, s66, 0x80000
	s_addc_u32 s67, s67, 0
	s_mov_b32 m0, s71
	v_lshl_add_u64 v[240:241], s[66:67], 0, v[0:1]
	ds_read_b128 v[192:195], v141 offset:32768
	ds_read_b128 v[196:199], v141 offset:33792
	ds_read_b128 v[200:203], v141 offset:34816
	ds_read_b128 v[204:207], v141 offset:35840
	ds_read_b128 v[208:211], v141 offset:36864
	ds_read_b128 v[222:225], v141 offset:37888
	ds_read_b128 v[226:229], v141 offset:38912
	ds_read_b128 v[230:233], v141 offset:39936
	global_load_lds_dwordx4 v[240:241], off
	v_lshl_add_u64 v[240:241], s[66:67], 0, v[130:131]
	s_mov_b32 m0, s72
	s_nop 0
	global_load_lds_dwordx4 v[240:241], off
	s_waitcnt vmcnt(8)
	s_waitcnt lgkmcnt(0)
	s_barrier
	s_setprio 1
	s_waitcnt lgkmcnt(0)
	v_mfma_f32_16x16x32_bf16 v[126:129], v[142:145], v[192:195], v[126:129]
	v_mfma_f32_16x16x32_bf16 v[118:121], v[168:171], v[192:195], v[118:121]
	v_mfma_f32_16x16x32_bf16 v[110:113], v[142:145], v[200:203], v[110:113]
	v_mfma_f32_16x16x32_bf16 v[102:105], v[168:171], v[200:203], v[102:105]
	v_mfma_f32_16x16x32_bf16 v[94:97], v[142:145], v[208:211], v[94:97]
	v_mfma_f32_16x16x32_bf16 v[86:89], v[168:171], v[208:211], v[86:89]
	v_mfma_f32_16x16x32_bf16 v[78:81], v[142:145], v[226:229], v[78:81]
	v_mfma_f32_16x16x32_bf16 v[70:73], v[168:171], v[226:229], v[70:73]
	s_setprio 0
	s_setprio 1
	v_mfma_f32_16x16x32_bf16 v[126:129], v[164:167], v[196:199], v[126:129]
	v_mfma_f32_16x16x32_bf16 v[118:121], v[172:175], v[196:199], v[118:121]
	v_mfma_f32_16x16x32_bf16 v[110:113], v[164:167], v[204:207], v[110:113]
	v_mfma_f32_16x16x32_bf16 v[102:105], v[172:175], v[204:207], v[102:105]
	v_mfma_f32_16x16x32_bf16 v[94:97], v[164:167], v[222:225], v[94:97]
	v_mfma_f32_16x16x32_bf16 v[86:89], v[172:175], v[222:225], v[86:89]
	v_mfma_f32_16x16x32_bf16 v[78:81], v[164:167], v[230:233], v[78:81]
	v_mfma_f32_16x16x32_bf16 v[70:73], v[172:175], v[230:233], v[70:73]
	s_setprio 0
	s_setprio 1
	v_mfma_f32_16x16x32_bf16 v[122:125], v[176:179], v[192:195], v[122:125]
	v_mfma_f32_16x16x32_bf16 v[114:117], v[184:187], v[192:195], v[114:117]
	v_mfma_f32_16x16x32_bf16 v[106:109], v[176:179], v[200:203], v[106:109]
	v_mfma_f32_16x16x32_bf16 v[98:101], v[184:187], v[200:203], v[98:101]
	v_mfma_f32_16x16x32_bf16 v[90:93], v[176:179], v[208:211], v[90:93]
	v_mfma_f32_16x16x32_bf16 v[82:85], v[184:187], v[208:211], v[82:85]
	v_mfma_f32_16x16x32_bf16 v[74:77], v[176:179], v[226:229], v[74:77]
	v_mfma_f32_16x16x32_bf16 v[66:69], v[184:187], v[226:229], v[66:69]
	s_setprio 0
	s_setprio 1
	v_mfma_f32_16x16x32_bf16 v[122:125], v[180:183], v[196:199], v[122:125]
	v_mfma_f32_16x16x32_bf16 v[114:117], v[188:191], v[196:199], v[114:117]
	v_mfma_f32_16x16x32_bf16 v[106:109], v[180:183], v[204:207], v[106:109]
	v_mfma_f32_16x16x32_bf16 v[98:101], v[188:191], v[204:207], v[98:101]
	v_mfma_f32_16x16x32_bf16 v[90:93], v[180:183], v[222:225], v[90:93]
	v_mfma_f32_16x16x32_bf16 v[82:85], v[188:191], v[222:225], v[82:85]
	v_mfma_f32_16x16x32_bf16 v[74:77], v[180:183], v[230:233], v[74:77]
	v_mfma_f32_16x16x32_bf16 v[66:69], v[188:191], v[230:233], v[66:69]
	s_setprio 0
	s_barrier
; #define PG8_STAGE(bufoff, gbase) do { _Pragma("unroll") for (int _i = 0; _i < 2; ++_i) \
;         __builtin_amdgcn_global_load_lds((const unsigned*)((const char*)(gbase) + voffA[_i]), (LAS unsigned*)(lds + (bufoff) + ldsw + _i * 8192), 16, 0, 0); } while (0)
; #define PG8_LDA(dst, b, h) do { _Pragma("unroll") for (int m = 0; m < 4; ++m) _Pragma("unroll") for (int k = 0; k < 2; ++k) dst[m][k] = *(const LAS bf16x8*)(lds + PG8_SA(b, h) + aoff + m * 2048 + k * 1024); } while (0)
; #define PG8_MMA(ai, bj, At, Bt) do { __builtin_amdgcn_s_setprio(1); _Pragma("unroll") for (int m = 0; m < 4; ++m) _Pragma("unroll") for (int n = 0; n < 2; ++n) _Pragma("unroll") for (int k = 0; k < 2; ++k) \
;         acc[ai][bj][m][n] = __builtin_amdgcn_mfma_f32_16x16x32_bf16(Bt[n][k], At[m][k], acc[ai][bj][m][n], 0, 0, 0); __builtin_amdgcn_s_setprio(0); } while (0)
; #define PG8_WAIT_V(n) asm volatile("s_waitcnt vmcnt(" #n ")" ::: "memory")
; #define PG8_WAIT_L(n) asm volatile("s_waitcnt lgkmcnt(" #n ")" ::: "memory")
; #define PG8_BAR __builtin_amdgcn_s_barrier()
; #define PG8_SCHED __builtin_amdgcn_sched_barrier(0)
; template <class Epi, class Sched>
; __device__ __forceinline__ void gemm_phase(LAS unsigned char* lds, const Gemm g, const Sched& S, const Epi& E) {
;     ...
;             PG8_LDA(At, 1, 1); PG8_STAGE(PG8_SB(1, 0), b3); PG8_STAGE(PG8_SB(1, 1), b3 + hstep); PG8_STAGE(PG8_SA(1, 0), a3);
;             PG8_WAIT_V(8); PG8_WAIT_L(0); PG8_BAR; PG8_MMA(1, 0, At, B0); PG8_MMA(1, 1, At, B1); PG8_BAR; PG8_SCHED;
;         }
	s_add_i32 s66, s99, s57
	v_lshl_add_u64 v[136:137], v[136:137], 0, s[26:27]
	s_mov_b32 m0, s66
	ds_read_b128 v[192:195], v141 offset:49152
	ds_read_b128 v[196:199], v141 offset:50176
	ds_read_b128 v[200:203], v141 offset:51200
	ds_read_b128 v[204:207], v141 offset:52224
	ds_read_b128 v[208:211], v141 offset:53248
	ds_read_b128 v[222:225], v141 offset:54272
	ds_read_b128 v[226:229], v141 offset:55296
	ds_read_b128 v[230:233], v141 offset:56320
	global_load_lds_dwordx4 v[136:137], off
	s_add_i32 m0, s66, 0x2000
	s_add_u32 s64, s64, 0x80080
	v_lshl_add_u64 v[136:137], v[234:235], 0, s[26:27]
	s_addc_u32 s65, s65, 0
	s_add_i32 s66, s91, s57
	global_load_lds_dwordx4 v[136:137], off
	v_lshl_add_u64 v[136:137], s[64:65], 0, v[0:1]
	s_mov_b32 m0, s66
	s_nop 0
	global_load_lds_dwordx4 v[136:137], off
	v_lshl_add_u64 v[136:137], s[64:65], 0, v[130:131]
	s_add_i32 m0, s66, 0x2000
	s_nop 0
	global_load_lds_dwordx4 v[136:137], off
	v_lshl_add_u64 v[136:137], v[236:237], 0, s[26:27]
	s_mov_b32 m0, s73
	s_nop 0
	global_load_lds_dwordx4 v[136:137], off
	v_lshl_add_u64 v[136:137], v[238:239], 0, s[26:27]
	s_mov_b32 m0, s74
	s_nop 0
	global_load_lds_dwordx4 v[136:137], off
	s_waitcnt vmcnt(8)
	s_waitcnt lgkmcnt(0)
	s_barrier
	s_setprio 1
	s_waitcnt lgkmcnt(0)
	v_mfma_f32_16x16x32_bf16 v[62:65], v[142:145], v[192:195], v[62:65]
	v_mfma_f32_16x16x32_bf16 v[54:57], v[168:171], v[192:195], v[54:57]
	v_mfma_f32_16x16x32_bf16 v[46:49], v[142:145], v[200:203], v[46:49]
	v_mfma_f32_16x16x32_bf16 v[38:41], v[168:171], v[200:203], v[38:41]
	v_mfma_f32_16x16x32_bf16 v[30:33], v[142:145], v[208:211], v[30:33]
	v_mfma_f32_16x16x32_bf16 v[22:25], v[168:171], v[208:211], v[22:25]
	v_mfma_f32_16x16x32_bf16 v[14:17], v[142:145], v[226:229], v[14:17]
	v_mfma_f32_16x16x32_bf16 v[6:9], v[168:171], v[226:229], v[6:9]
	s_setprio 0
	s_setprio 1
	v_mfma_f32_16x16x32_bf16 v[62:65], v[164:167], v[196:199], v[62:65]
	v_mfma_f32_16x16x32_bf16 v[54:57], v[172:175], v[196:199], v[54:57]
	v_mfma_f32_16x16x32_bf16 v[46:49], v[164:167], v[204:207], v[46:49]
	v_mfma_f32_16x16x32_bf16 v[38:41], v[172:175], v[204:207], v[38:41]
	v_mfma_f32_16x16x32_bf16 v[30:33], v[164:167], v[222:225], v[30:33]
	v_mfma_f32_16x16x32_bf16 v[22:25], v[172:175], v[222:225], v[22:25]
	v_mfma_f32_16x16x32_bf16 v[14:17], v[164:167], v[230:233], v[14:17]
	v_mfma_f32_16x16x32_bf16 v[6:9], v[172:175], v[230:233], v[6:9]
	s_setprio 0
	s_setprio 1
	v_mfma_f32_16x16x32_bf16 v[58:61], v[176:179], v[192:195], v[58:61]
	v_mfma_f32_16x16x32_bf16 v[50:53], v[184:187], v[192:195], v[50:53]
	v_mfma_f32_16x16x32_bf16 v[42:45], v[176:179], v[200:203], v[42:45]
	v_mfma_f32_16x16x32_bf16 v[34:37], v[184:187], v[200:203], v[34:37]
	v_mfma_f32_16x16x32_bf16 v[26:29], v[176:179], v[208:211], v[26:29]
	v_mfma_f32_16x16x32_bf16 v[18:21], v[184:187], v[208:211], v[18:21]
	v_mfma_f32_16x16x32_bf16 v[10:13], v[176:179], v[226:229], v[10:13]
	v_mfma_f32_16x16x32_bf16 v[2:5], v[184:187], v[226:229], v[2:5]
	s_setprio 0
	s_setprio 1
	v_mfma_f32_16x16x32_bf16 v[58:61], v[180:183], v[196:199], v[58:61]
	v_mfma_f32_16x16x32_bf16 v[50:53], v[188:191], v[196:199], v[50:53]
	v_mfma_f32_16x16x32_bf16 v[42:45], v[180:183], v[204:207], v[42:45]
	v_mfma_f32_16x16x32_bf16 v[34:37], v[188:191], v[204:207], v[34:37]
	v_mfma_f32_16x16x32_bf16 v[26:29], v[180:183], v[222:225], v[26:29]
	v_mfma_f32_16x16x32_bf16 v[18:21], v[188:191], v[222:225], v[18:21]
	v_mfma_f32_16x16x32_bf16 v[10:13], v[180:183], v[230:233], v[10:13]
	v_mfma_f32_16x16x32_bf16 v[2:5], v[188:191], v[230:233], v[2:5]
	s_setprio 0
	s_barrier
	s_add_i32 s90, s90, 2
	s_add_u32 s62, s62, 0x100
	s_addc_u32 s63, s63, 0
	s_add_u32 s88, s88, 0x100
	s_addc_u32 s89, s89, 0
	s_cmp_gt_u32 s90, 29
	s_cbranch_scc0 .LBB0_51
	s_and_b64 vcc, exec, s[20:21]
	s_cbranch_vccz .LBB0_54
	s_barrier

; #define PG8_STAGE(bufoff, gbase) do { _Pragma("unroll") for (int _i = 0; _i < 2; ++_i) \
;         __builtin_amdgcn_global_load_lds((const unsigned*)((const char*)(gbase) + voffA[_i]), (LAS unsigned*)(lds + (bufoff) + ldsw + _i * 8192), 16, 0, 0); } while (0)
; #define PG8_LDA(dst, b, h) do { _Pragma("unroll") for (int m = 0; m < 4; ++m) _Pragma("unroll") for (int k = 0; k < 2; ++k) dst[m][k] = *(const LAS bf16x8*)(lds + PG8_SA(b, h) + aoff + m * 2048 + k * 1024); } while (0)
; #define PG8_LDB(dst, b, h) do { _Pragma("unroll") for (int n = 0; n < 2; ++n) _Pragma("unroll") for (int k = 0; k < 2; ++k) dst[n][k] = *(const LAS bf16x8*)(lds + PG8_SB(b, h) + boff + n * 2048 + k * 1024); } while (0)
; #define PG8_MMA(ai, bj, At, Bt) do { __builtin_amdgcn_s_setprio(1); _Pragma("unroll") for (int m = 0; m < 4; ++m) _Pragma("unroll") for (int n = 0; n < 2; ++n) _Pragma("unroll") for (int k = 0; k < 2; ++k) \
;         acc[ai][bj][m][n] = __builtin_amdgcn_mfma_f32_16x16x32_bf16(Bt[n][k], At[m][k], acc[ai][bj][m][n], 0, 0, 0); __builtin_amdgcn_s_setprio(0); } while (0)
; #define PG8_WAIT_V(n) asm volatile("s_waitcnt vmcnt(" #n ")" ::: "memory")
; #define PG8_WAIT_L(n) asm volatile("s_waitcnt lgkmcnt(" #n ")" ::: "memory")
; #define PG8_BAR __builtin_amdgcn_s_barrier()
; #define PG8_SCHED __builtin_amdgcn_sched_barrier(0)
; template <class Epi, class Sched>
; __device__ __forceinline__ void gemm_phase(LAS unsigned char* lds, const Gemm g, const Sched& S, const Epi& E) {
;     ...
;         for (int t = 0; t < nt; t += 2) {
;             const bool last = (t == nt - 2);
;             const char* a1 = cA + (size_t)(t + 1) * kstep;
;             const char* a2 = last ? nA : cA + (size_t)(t + 2) * kstep; const char* b2 = last ? nB : cB + (size_t)(t + 2) * kstep;
;             const char* a3 = a2 + kstep; const char* b3 = b2 + kstep;
;             PG8_LDB(B0, 0, 0); PG8_LDB(B1, 0, 1); PG8_SCHED; PG8_LDA(At, 0, 0); PG8_STAGE(PG8_SA(1, 1), a1 + hstep);
;             PG8_WAIT_V(8); PG8_WAIT_L(0); PG8_BAR; PG8_MMA(0, 0, At, B0); PG8_MMA(0, 1, At, B1); PG8_BAR; PG8_SCHED;
;             PG8_LDA(At, 0, 1); PG8_STAGE(PG8_SB(0, 0), b2); PG8_STAGE(PG8_SB(0, 1), b2 + hstep); PG8_STAGE(PG8_SA(0, 0), a2);
;             PG8_WAIT_V(8); PG8_WAIT_L(0); PG8_BAR; PG8_MMA(1, 0, At, B0); PG8_MMA(1, 1, At, B1); PG8_BAR; PG8_SCHED;
.LBB0_156:
	s_add_u32 s70, s68, 0xfff80080
	s_addc_u32 s71, s69, -1
	s_add_i32 s92, 0, 0x10000
	s_cmp_eq_u32 s91, 28
	s_cselect_b32 s73, s51, s71
	s_cselect_b32 s72, s67, s70
	v_add_u32_e32 v0, s92, v170
	s_cselect_b32 s71, s49, s90
	s_cselect_b32 s70, s88, s89
	s_add_i32 s94, 0, 0x14000
	ds_read_b128 v[166:169], v0
	ds_read_b128 v[174:177], v0 offset:1024
	ds_read_b128 v[178:181], v0 offset:2048
	ds_read_b128 v[182:185], v0 offset:3072
	v_add_u32_e32 v0, s94, v170
	ds_read_b128 v[186:189], v0
	ds_read_b128 v[190:193], v0 offset:1024
	ds_read_b128 v[194:197], v0 offset:2048
	ds_read_b128 v[198:201], v0 offset:3072
	v_lshl_add_u64 v[210:211], s[68:69], 0, v[138:139]
	s_add_i32 m0, s60, 0xc000
	ds_read_b128 v[202:205], v171
	ds_read_b128 v[206:209], v171 offset:1024
	ds_read_b128 v[222:225], v171 offset:2048
	ds_read_b128 v[226:229], v171 offset:3072
	ds_read_b128 v[230:233], v171 offset:4096
	ds_read_b128 v[234:237], v171 offset:5120
	ds_read_b128 v[238:241], v171 offset:6144
	ds_read_b128 v[242:245], v171 offset:7168
	global_load_lds_dwordx4 v[210:211], off
	v_lshl_add_u64 v[210:211], s[68:69], 0, v[140:141]
	s_add_i32 m0, s60, 0xe000
	s_nop 0
	global_load_lds_dwordx4 v[210:211], off
	s_waitcnt vmcnt(8)
	s_waitcnt lgkmcnt(0)
	s_barrier
	s_setprio 1
	s_waitcnt lgkmcnt(0)
	v_mfma_f32_16x16x32_bf16 v[126:129], v[166:169], v[202:205], v[126:129]
	v_mfma_f32_16x16x32_bf16 v[122:125], v[178:181], v[202:205], v[122:125]
	v_mfma_f32_16x16x32_bf16 v[110:113], v[166:169], v[222:225], v[110:113]
	v_mfma_f32_16x16x32_bf16 v[106:109], v[178:181], v[222:225], v[106:109]
	v_mfma_f32_16x16x32_bf16 v[94:97], v[166:169], v[230:233], v[94:97]
	v_mfma_f32_16x16x32_bf16 v[90:93], v[178:181], v[230:233], v[90:93]
	v_mfma_f32_16x16x32_bf16 v[78:81], v[166:169], v[238:241], v[78:81]
	v_mfma_f32_16x16x32_bf16 v[74:77], v[178:181], v[238:241], v[74:77]
	s_setprio 0
	s_setprio 1
	v_mfma_f32_16x16x32_bf16 v[126:129], v[174:177], v[206:209], v[126:129]
	v_mfma_f32_16x16x32_bf16 v[122:125], v[182:185], v[206:209], v[122:125]
	v_mfma_f32_16x16x32_bf16 v[110:113], v[174:177], v[226:229], v[110:113]
	v_mfma_f32_16x16x32_bf16 v[106:109], v[182:185], v[226:229], v[106:109]
	v_mfma_f32_16x16x32_bf16 v[94:97], v[174:177], v[234:237], v[94:97]
	v_mfma_f32_16x16x32_bf16 v[90:93], v[182:185], v[234:237], v[90:93]
	v_mfma_f32_16x16x32_bf16 v[78:81], v[174:177], v[242:245], v[78:81]
	v_mfma_f32_16x16x32_bf16 v[74:77], v[182:185], v[242:245], v[74:77]
	s_setprio 0
	s_setprio 1
	v_mfma_f32_16x16x32_bf16 v[118:121], v[186:189], v[202:205], v[118:121]
	v_mfma_f32_16x16x32_bf16 v[114:117], v[194:197], v[202:205], v[114:117]
	v_mfma_f32_16x16x32_bf16 v[102:105], v[186:189], v[222:225], v[102:105]
	v_mfma_f32_16x16x32_bf16 v[98:101], v[194:197], v[222:225], v[98:101]
	v_mfma_f32_16x16x32_bf16 v[86:89], v[186:189], v[230:233], v[86:89]
	v_mfma_f32_16x16x32_bf16 v[82:85], v[194:197], v[230:233], v[82:85]
	v_mfma_f32_16x16x32_bf16 v[70:73], v[186:189], v[238:241], v[70:73]
	v_mfma_f32_16x16x32_bf16 v[66:69], v[194:197], v[238:241], v[66:69]
	s_setprio 0
	s_setprio 1
	v_mfma_f32_16x16x32_bf16 v[118:121], v[190:193], v[206:209], v[118:121]
	v_mfma_f32_16x16x32_bf16 v[114:117], v[198:201], v[206:209], v[114:117]
	v_mfma_f32_16x16x32_bf16 v[102:105], v[190:193], v[226:229], v[102:105]
	v_mfma_f32_16x16x32_bf16 v[98:101], v[198:201], v[226:229], v[98:101]
	v_mfma_f32_16x16x32_bf16 v[86:89], v[190:193], v[234:237], v[86:89]
	v_mfma_f32_16x16x32_bf16 v[82:85], v[198:201], v[234:237], v[82:85]
	v_mfma_f32_16x16x32_bf16 v[70:73], v[190:193], v[242:245], v[70:73]
	v_mfma_f32_16x16x32_bf16 v[66:69], v[198:201], v[242:245], v[66:69]
	s_setprio 0
	s_barrier
	s_add_i32 s92, s92, s84
	v_lshl_add_u64 v[210:211], s[70:71], 0, v[132:133]
	s_mov_b32 m0, s92
	ds_read_b128 v[202:205], v171 offset:16384
	ds_read_b128 v[206:209], v171 offset:17408
	ds_read_b128 v[222:225], v171 offset:18432
	ds_read_b128 v[226:229], v171 offset:19456
	ds_read_b128 v[230:233], v171 offset:20480
	ds_read_b128 v[234:237], v171 offset:21504
	ds_read_b128 v[238:241], v171 offset:22528
	ds_read_b128 v[242:245], v171 offset:23552
	global_load_lds_dwordx4 v[210:211], off
	s_add_i32 m0, s92, 0x2000
	s_add_u32 s92, s70, 0x80000
	v_lshl_add_u64 v[216:217], s[70:71], 0, v[130:131]
	s_addc_u32 s93, s71, 0
	s_add_i32 s94, s94, s84
	global_load_lds_dwordx4 v[216:217], off
	v_lshl_add_u64 v[246:247], s[92:93], 0, v[132:133]
	s_mov_b32 m0, s94
	v_lshl_add_u64 v[248:249], s[72:73], 0, v[130:131]
	global_load_lds_dwordx4 v[246:247], off
	v_lshl_add_u64 v[246:247], s[92:93], 0, v[130:131]
	s_add_i32 m0, s94, 0x2000
	s_nop 0
	global_load_lds_dwordx4 v[246:247], off
	v_lshl_add_u64 v[246:247], s[72:73], 0, v[132:133]
	s_mov_b32 m0, s60
	s_nop 0
	global_load_lds_dwordx4 v[246:247], off
	s_mov_b32 m0, s61
	s_nop 0
	global_load_lds_dwordx4 v[248:249], off
	s_waitcnt vmcnt(8)
	s_waitcnt lgkmcnt(0)
	s_barrier
; #define PG8_STAGE(bufoff, gbase) do { _Pragma("unroll") for (int _i = 0; _i < 2; ++_i) \
;         __builtin_amdgcn_global_load_lds((const unsigned*)((const char*)(gbase) + voffA[_i]), (LAS unsigned*)(lds + (bufoff) + ldsw + _i * 8192), 16, 0, 0); } while (0)
; #define PG8_LDA(dst, b, h) do { _Pragma("unroll") for (int m = 0; m < 4; ++m) _Pragma("unroll") for (int k = 0; k < 2; ++k) dst[m][k] = *(const LAS bf16x8*)(lds + PG8_SA(b, h) + aoff + m * 2048 + k * 1024); } while (0)
; #define PG8_LDB(dst, b, h) do { _Pragma("unroll") for (int n = 0; n < 2; ++n) _Pragma("unroll") for (int k = 0; k < 2; ++k) dst[n][k] = *(const LAS bf16x8*)(lds + PG8_SB(b, h) + boff + n * 2048 + k * 1024); } while (0)
; #define PG8_MMA(ai, bj, At, Bt) do { __builtin_amdgcn_s_setprio(1); _Pragma("unroll") for (int m = 0; m < 4; ++m) _Pragma("unroll") for (int n = 0; n < 2; ++n) _Pragma("unroll") for (int k = 0; k < 2; ++k) \
;         acc[ai][bj][m][n] = __builtin_amdgcn_mfma_f32_16x16x32_bf16(Bt[n][k], At[m][k], acc[ai][bj][m][n], 0, 0, 0); __builtin_amdgcn_s_setprio(0); } while (0)
; #define PG8_WAIT_V(n) asm volatile("s_waitcnt vmcnt(" #n ")" ::: "memory")
; #define PG8_WAIT_L(n) asm volatile("s_waitcnt lgkmcnt(" #n ")" ::: "memory")
; #define PG8_BAR __builtin_amdgcn_s_barrier()
; #define PG8_SCHED __builtin_amdgcn_sched_barrier(0)
; template <class Epi, class Sched>
; __device__ __forceinline__ void gemm_phase(LAS unsigned char* lds, const Gemm g, const Sched& S, const Epi& E) {
;     ...
;             PG8_WAIT_V(8); PG8_WAIT_L(0); PG8_BAR; PG8_MMA(1, 0, At, B0); PG8_MMA(1, 1, At, B1); PG8_BAR; PG8_SCHED;
;             PG8_LDB(B0, 1, 0); PG8_LDB(B1, 1, 1); PG8_SCHED; PG8_LDA(At, 1, 0); PG8_STAGE(PG8_SA(0, 1), a2 + hstep);
;             PG8_WAIT_V(8); PG8_WAIT_L(0); PG8_BAR; PG8_MMA(0, 0, At, B0); PG8_MMA(0, 1, At, B1); PG8_BAR; PG8_SCHED;
	s_setprio 1
	s_waitcnt lgkmcnt(0)
	v_mfma_f32_16x16x32_bf16 v[62:65], v[166:169], v[202:205], v[62:65]
	v_mfma_f32_16x16x32_bf16 v[58:61], v[178:181], v[202:205], v[58:61]
	v_mfma_f32_16x16x32_bf16 v[46:49], v[166:169], v[222:225], v[46:49]
	v_mfma_f32_16x16x32_bf16 v[42:45], v[178:181], v[222:225], v[42:45]
	v_mfma_f32_16x16x32_bf16 v[30:33], v[166:169], v[230:233], v[30:33]
	v_mfma_f32_16x16x32_bf16 v[26:29], v[178:181], v[230:233], v[26:29]
	v_mfma_f32_16x16x32_bf16 v[14:17], v[166:169], v[238:241], v[14:17]
	v_mfma_f32_16x16x32_bf16 v[10:13], v[178:181], v[238:241], v[10:13]
	s_setprio 0
	s_setprio 1
	v_mfma_f32_16x16x32_bf16 v[62:65], v[174:177], v[206:209], v[62:65]
	v_mfma_f32_16x16x32_bf16 v[58:61], v[182:185], v[206:209], v[58:61]
	v_mfma_f32_16x16x32_bf16 v[46:49], v[174:177], v[226:229], v[46:49]
	v_mfma_f32_16x16x32_bf16 v[42:45], v[182:185], v[226:229], v[42:45]
	v_mfma_f32_16x16x32_bf16 v[30:33], v[174:177], v[234:237], v[30:33]
	v_mfma_f32_16x16x32_bf16 v[26:29], v[182:185], v[234:237], v[26:29]
	v_mfma_f32_16x16x32_bf16 v[14:17], v[174:177], v[242:245], v[14:17]
	v_mfma_f32_16x16x32_bf16 v[10:13], v[182:185], v[242:245], v[10:13]
	s_setprio 0
	s_setprio 1
	v_mfma_f32_16x16x32_bf16 v[54:57], v[186:189], v[202:205], v[54:57]
	v_mfma_f32_16x16x32_bf16 v[50:53], v[194:197], v[202:205], v[50:53]
	v_mfma_f32_16x16x32_bf16 v[38:41], v[186:189], v[222:225], v[38:41]
	v_mfma_f32_16x16x32_bf16 v[34:37], v[194:197], v[222:225], v[34:37]
	v_mfma_f32_16x16x32_bf16 v[22:25], v[186:189], v[230:233], v[22:25]
	v_mfma_f32_16x16x32_bf16 v[18:21], v[194:197], v[230:233], v[18:21]
	v_mfma_f32_16x16x32_bf16 v[6:9], v[186:189], v[238:241], v[6:9]
	v_mfma_f32_16x16x32_bf16 v[2:5], v[194:197], v[238:241], v[2:5]
	s_setprio 0
	s_setprio 1
	v_mfma_f32_16x16x32_bf16 v[54:57], v[190:193], v[206:209], v[54:57]
	v_mfma_f32_16x16x32_bf16 v[50:53], v[198:201], v[206:209], v[50:53]
	v_mfma_f32_16x16x32_bf16 v[38:41], v[190:193], v[226:229], v[38:41]
	v_mfma_f32_16x16x32_bf16 v[34:37], v[198:201], v[226:229], v[34:37]
	v_mfma_f32_16x16x32_bf16 v[22:25], v[190:193], v[234:237], v[22:25]
	v_mfma_f32_16x16x32_bf16 v[18:21], v[198:201], v[234:237], v[18:21]
	v_mfma_f32_16x16x32_bf16 v[6:9], v[190:193], v[242:245], v[6:9]
	v_mfma_f32_16x16x32_bf16 v[2:5], v[198:201], v[242:245], v[2:5]
	s_setprio 0
	s_barrier
	v_add_u32_e32 v0, s99, v170
	s_add_i32 s92, 0, 0x1c000
	ds_read_b128 v[166:169], v0
	ds_read_b128 v[174:177], v0 offset:1024
	ds_read_b128 v[178:181], v0 offset:2048
	ds_read_b128 v[182:185], v0 offset:3072
	v_add_u32_e32 v0, s92, v170
	ds_read_b128 v[186:189], v0
	ds_read_b128 v[190:193], v0 offset:1024
	ds_read_b128 v[194:197], v0 offset:2048
	ds_read_b128 v[198:201], v0 offset:3072
	s_add_u32 s72, s72, 0x80000
	s_addc_u32 s73, s73, 0
	s_mov_b32 m0, s44
	v_lshl_add_u64 v[250:251], s[72:73], 0, v[132:133]
	ds_read_b128 v[202:205], v171 offset:32768
	ds_read_b128 v[206:209], v171 offset:33792
	ds_read_b128 v[222:225], v171 offset:34816
	ds_read_b128 v[226:229], v171 offset:35840
	ds_read_b128 v[230:233], v171 offset:36864
	ds_read_b128 v[234:237], v171 offset:37888
	ds_read_b128 v[238:241], v171 offset:38912
	ds_read_b128 v[242:245], v171 offset:39936
	global_load_lds_dwordx4 v[250:251], off
	v_lshl_add_u64 v[250:251], s[72:73], 0, v[130:131]
	s_mov_b32 m0, s45
	s_nop 0
	global_load_lds_dwordx4 v[250:251], off
	s_waitcnt vmcnt(8)
	s_waitcnt lgkmcnt(0)
	s_barrier
	s_setprio 1
	s_waitcnt lgkmcnt(0)
	v_mfma_f32_16x16x32_bf16 v[126:129], v[166:169], v[202:205], v[126:129]
	v_mfma_f32_16x16x32_bf16 v[122:125], v[178:181], v[202:205], v[122:125]
	v_mfma_f32_16x16x32_bf16 v[110:113], v[166:169], v[222:225], v[110:113]
	v_mfma_f32_16x16x32_bf16 v[106:109], v[178:181], v[222:225], v[106:109]
	v_mfma_f32_16x16x32_bf16 v[94:97], v[166:169], v[230:233], v[94:97]
	v_mfma_f32_16x16x32_bf16 v[90:93], v[178:181], v[230:233], v[90:93]
	v_mfma_f32_16x16x32_bf16 v[78:81], v[166:169], v[238:241], v[78:81]
	v_mfma_f32_16x16x32_bf16 v[74:77], v[178:181], v[238:241], v[74:77]
	s_setprio 0
	s_setprio 1
	v_mfma_f32_16x16x32_bf16 v[126:129], v[174:177], v[206:209], v[126:129]
	v_mfma_f32_16x16x32_bf16 v[122:125], v[182:185], v[206:209], v[122:125]
	v_mfma_f32_16x16x32_bf16 v[110:113], v[174:177], v[226:229], v[110:113]
	v_mfma_f32_16x16x32_bf16 v[106:109], v[182:185], v[226:229], v[106:109]
	v_mfma_f32_16x16x32_bf16 v[94:97], v[174:177], v[234:237], v[94:97]
	v_mfma_f32_16x16x32_bf16 v[90:93], v[182:185], v[234:237], v[90:93]
	v_mfma_f32_16x16x32_bf16 v[78:81], v[174:177], v[242:245], v[78:81]
	v_mfma_f32_16x16x32_bf16 v[74:77], v[182:185], v[242:245], v[74:77]
	s_setprio 0
	s_setprio 1
	v_mfma_f32_16x16x32_bf16 v[118:121], v[186:189], v[202:205], v[118:121]
	v_mfma_f32_16x16x32_bf16 v[114:117], v[194:197], v[202:205], v[114:117]
	v_mfma_f32_16x16x32_bf16 v[102:105], v[186:189], v[222:225], v[102:105]
	v_mfma_f32_16x16x32_bf16 v[98:101], v[194:197], v[222:225], v[98:101]
	v_mfma_f32_16x16x32_bf16 v[86:89], v[186:189], v[230:233], v[86:89]
	v_mfma_f32_16x16x32_bf16 v[82:85], v[194:197], v[230:233], v[82:85]
	v_mfma_f32_16x16x32_bf16 v[70:73], v[186:189], v[238:241], v[70:73]
	v_mfma_f32_16x16x32_bf16 v[66:69], v[194:197], v[238:241], v[66:69]
	s_setprio 0
	s_setprio 1
	v_mfma_f32_16x16x32_bf16 v[118:121], v[190:193], v[206:209], v[118:121]
	v_mfma_f32_16x16x32_bf16 v[114:117], v[198:201], v[206:209], v[114:117]
	v_mfma_f32_16x16x32_bf16 v[102:105], v[190:193], v[226:229], v[102:105]
	v_mfma_f32_16x16x32_bf16 v[98:101], v[198:201], v[226:229], v[98:101]
	v_mfma_f32_16x16x32_bf16 v[86:89], v[190:193], v[234:237], v[86:89]
	v_mfma_f32_16x16x32_bf16 v[82:85], v[198:201], v[234:237], v[82:85]
	v_mfma_f32_16x16x32_bf16 v[70:73], v[190:193], v[242:245], v[70:73]
	v_mfma_f32_16x16x32_bf16 v[66:69], v[198:201], v[242:245], v[66:69]
	s_setprio 0
	s_barrier
; #define PG8_STAGE(bufoff, gbase) do { _Pragma("unroll") for (int _i = 0; _i < 2; ++_i) \
;         __builtin_amdgcn_global_load_lds((const unsigned*)((const char*)(gbase) + voffA[_i]), (LAS unsigned*)(lds + (bufoff) + ldsw + _i * 8192), 16, 0, 0); } while (0)
; #define PG8_LDA(dst, b, h) do { _Pragma("unroll") for (int m = 0; m < 4; ++m) _Pragma("unroll") for (int k = 0; k < 2; ++k) dst[m][k] = *(const LAS bf16x8*)(lds + PG8_SA(b, h) + aoff + m * 2048 + k * 1024); } while (0)
; #define PG8_MMA(ai, bj, At, Bt) do { __builtin_amdgcn_s_setprio(1); _Pragma("unroll") for (int m = 0; m < 4; ++m) _Pragma("unroll") for (int n = 0; n < 2; ++n) _Pragma("unroll") for (int k = 0; k < 2; ++k) \
;         acc[ai][bj][m][n] = __builtin_amdgcn_mfma_f32_16x16x32_bf16(Bt[n][k], At[m][k], acc[ai][bj][m][n], 0, 0, 0); __builtin_amdgcn_s_setprio(0); } while (0)
; #define PG8_WAIT_V(n) asm volatile("s_waitcnt vmcnt(" #n ")" ::: "memory")
; #define PG8_WAIT_L(n) asm volatile("s_waitcnt lgkmcnt(" #n ")" ::: "memory")
; #define PG8_BAR __builtin_amdgcn_s_barrier()
; #define PG8_SCHED __builtin_amdgcn_sched_barrier(0)
; template <class Epi, class Sched>
; __device__ __forceinline__ void gemm_phase(LAS unsigned char* lds, const Gemm g, const Sched& S, const Epi& E) {
;     ...
;             PG8_LDA(At, 1, 1); PG8_STAGE(PG8_SB(1, 0), b3); PG8_STAGE(PG8_SB(1, 1), b3 + hstep); PG8_STAGE(PG8_SA(1, 0), a3);
;             PG8_WAIT_V(8); PG8_WAIT_L(0); PG8_BAR; PG8_MMA(1, 0, At, B0); PG8_MMA(1, 1, At, B1); PG8_BAR; PG8_SCHED;
;         }
	s_add_i32 s72, s99, s84
	v_lshl_add_u64 v[210:211], v[210:211], 0, s[26:27]
	s_mov_b32 m0, s72
	ds_read_b128 v[202:205], v171 offset:49152
	ds_read_b128 v[206:209], v171 offset:50176
	ds_read_b128 v[222:225], v171 offset:51200
	ds_read_b128 v[226:229], v171 offset:52224
	ds_read_b128 v[230:233], v171 offset:53248
	ds_read_b128 v[234:237], v171 offset:54272
	ds_read_b128 v[238:241], v171 offset:55296
	ds_read_b128 v[242:245], v171 offset:56320
	global_load_lds_dwordx4 v[210:211], off
	s_add_i32 m0, s72, 0x2000
	s_add_u32 s70, s70, 0x80080
	v_lshl_add_u64 v[210:211], v[216:217], 0, s[26:27]
	s_addc_u32 s71, s71, 0
	s_add_i32 s72, s92, s84
	global_load_lds_dwordx4 v[210:211], off
	v_lshl_add_u64 v[210:211], s[70:71], 0, v[132:133]
	s_mov_b32 m0, s72
	s_nop 0
	global_load_lds_dwordx4 v[210:211], off
	v_lshl_add_u64 v[210:211], s[70:71], 0, v[130:131]
	s_add_i32 m0, s72, 0x2000
	s_nop 0
	global_load_lds_dwordx4 v[210:211], off
	v_lshl_add_u64 v[210:211], v[246:247], 0, s[26:27]
	s_mov_b32 m0, s38
	s_nop 0
	global_load_lds_dwordx4 v[210:211], off
	v_lshl_add_u64 v[210:211], v[248:249], 0, s[26:27]
	s_mov_b32 m0, s39
	s_nop 0
	global_load_lds_dwordx4 v[210:211], off
	s_waitcnt vmcnt(8)
	s_waitcnt lgkmcnt(0)
	s_barrier
	s_setprio 1
	s_waitcnt lgkmcnt(0)
	v_mfma_f32_16x16x32_bf16 v[62:65], v[166:169], v[202:205], v[62:65]
	v_mfma_f32_16x16x32_bf16 v[58:61], v[178:181], v[202:205], v[58:61]
	v_mfma_f32_16x16x32_bf16 v[46:49], v[166:169], v[222:225], v[46:49]
	v_mfma_f32_16x16x32_bf16 v[42:45], v[178:181], v[222:225], v[42:45]
	v_mfma_f32_16x16x32_bf16 v[30:33], v[166:169], v[230:233], v[30:33]
	v_mfma_f32_16x16x32_bf16 v[26:29], v[178:181], v[230:233], v[26:29]
	v_mfma_f32_16x16x32_bf16 v[14:17], v[166:169], v[238:241], v[14:17]
	v_mfma_f32_16x16x32_bf16 v[10:13], v[178:181], v[238:241], v[10:13]
	s_setprio 0
	s_setprio 1
	v_mfma_f32_16x16x32_bf16 v[62:65], v[174:177], v[206:209], v[62:65]
	v_mfma_f32_16x16x32_bf16 v[58:61], v[182:185], v[206:209], v[58:61]
	v_mfma_f32_16x16x32_bf16 v[46:49], v[174:177], v[226:229], v[46:49]
	v_mfma_f32_16x16x32_bf16 v[42:45], v[182:185], v[226:229], v[42:45]
	v_mfma_f32_16x16x32_bf16 v[30:33], v[174:177], v[234:237], v[30:33]
	v_mfma_f32_16x16x32_bf16 v[26:29], v[182:185], v[234:237], v[26:29]
	v_mfma_f32_16x16x32_bf16 v[14:17], v[174:177], v[242:245], v[14:17]
	v_mfma_f32_16x16x32_bf16 v[10:13], v[182:185], v[242:245], v[10:13]
	s_setprio 0
	s_setprio 1
	v_mfma_f32_16x16x32_bf16 v[54:57], v[186:189], v[202:205], v[54:57]
	v_mfma_f32_16x16x32_bf16 v[50:53], v[194:197], v[202:205], v[50:53]
	v_mfma_f32_16x16x32_bf16 v[38:41], v[186:189], v[222:225], v[38:41]
	v_mfma_f32_16x16x32_bf16 v[34:37], v[194:197], v[222:225], v[34:37]
	v_mfma_f32_16x16x32_bf16 v[22:25], v[186:189], v[230:233], v[22:25]
	v_mfma_f32_16x16x32_bf16 v[18:21], v[194:197], v[230:233], v[18:21]
	v_mfma_f32_16x16x32_bf16 v[6:9], v[186:189], v[238:241], v[6:9]
	v_mfma_f32_16x16x32_bf16 v[2:5], v[194:197], v[238:241], v[2:5]
	s_setprio 0
	s_setprio 1
	v_mfma_f32_16x16x32_bf16 v[54:57], v[190:193], v[206:209], v[54:57]
	v_mfma_f32_16x16x32_bf16 v[50:53], v[198:201], v[206:209], v[50:53]
	v_mfma_f32_16x16x32_bf16 v[38:41], v[190:193], v[226:229], v[38:41]
	v_mfma_f32_16x16x32_bf16 v[34:37], v[198:201], v[226:229], v[34:37]
	v_mfma_f32_16x16x32_bf16 v[22:25], v[190:193], v[234:237], v[22:25]
	v_mfma_f32_16x16x32_bf16 v[18:21], v[198:201], v[234:237], v[18:21]
	v_mfma_f32_16x16x32_bf16 v[6:9], v[190:193], v[242:245], v[6:9]
	v_mfma_f32_16x16x32_bf16 v[2:5], v[198:201], v[242:245], v[2:5]
	s_setprio 0
	s_barrier
	s_add_i32 s91, s91, 2
	s_add_u32 s68, s68, 0x100
	s_addc_u32 s69, s69, 0
	s_add_u32 s89, s89, 0x100
	s_addc_u32 s90, s90, 0
	s_cmp_gt_u32 s91, 29
	s_cbranch_scc0 .LBB0_156
	s_and_b64 vcc, exec, s[46:47]
	s_cbranch_vccz .LBB0_159
	s_barrier

; #define PG8_STAGE(bufoff, gbase) do { _Pragma("unroll") for (int _i = 0; _i < 2; ++_i) \
;         __builtin_amdgcn_global_load_lds((const unsigned*)((const char*)(gbase) + voffA[_i]), (LAS unsigned*)(lds + (bufoff) + ldsw + _i * 8192), 16, 0, 0); } while (0)
; #define PG8_LDA(dst, b, h) do { _Pragma("unroll") for (int m = 0; m < 4; ++m) _Pragma("unroll") for (int k = 0; k < 2; ++k) dst[m][k] = *(const LAS bf16x8*)(lds + PG8_SA(b, h) + aoff + m * 2048 + k * 1024); } while (0)
; #define PG8_LDB(dst, b, h) do { _Pragma("unroll") for (int n = 0; n < 2; ++n) _Pragma("unroll") for (int k = 0; k < 2; ++k) dst[n][k] = *(const LAS bf16x8*)(lds + PG8_SB(b, h) + boff + n * 2048 + k * 1024); } while (0)
; #define PG8_MMA(ai, bj, At, Bt) do { __builtin_amdgcn_s_setprio(1); _Pragma("unroll") for (int m = 0; m < 4; ++m) _Pragma("unroll") for (int n = 0; n < 2; ++n) _Pragma("unroll") for (int k = 0; k < 2; ++k) \
;         acc[ai][bj][m][n] = __builtin_amdgcn_mfma_f32_16x16x32_bf16(Bt[n][k], At[m][k], acc[ai][bj][m][n], 0, 0, 0); __builtin_amdgcn_s_setprio(0); } while (0)
; #define PG8_WAIT_V(n) asm volatile("s_waitcnt vmcnt(" #n ")" ::: "memory")
; #define PG8_WAIT_L(n) asm volatile("s_waitcnt lgkmcnt(" #n ")" ::: "memory")
; #define PG8_BAR __builtin_amdgcn_s_barrier()
; #define PG8_SCHED __builtin_amdgcn_sched_barrier(0)
; template <class Epi, class Sched>
; __device__ __forceinline__ void gemm_phase(LAS unsigned char* lds, const Gemm g, const Sched& S, const Epi& E) {
;     ...
;         for (int t = 0; t < nt; t += 2) {
;             const bool last = (t == nt - 2);
;             const char* a1 = cA + (size_t)(t + 1) * kstep;
;             const char* a2 = last ? nA : cA + (size_t)(t + 2) * kstep; const char* b2 = last ? nB : cB + (size_t)(t + 2) * kstep;
;             const char* a3 = a2 + kstep; const char* b3 = b2 + kstep;
;             PG8_LDB(B0, 0, 0); PG8_LDB(B1, 0, 1); PG8_SCHED; PG8_LDA(At, 0, 0); PG8_STAGE(PG8_SA(1, 1), a1 + hstep);
;             PG8_WAIT_V(8); PG8_WAIT_L(0); PG8_BAR; PG8_MMA(0, 0, At, B0); PG8_MMA(0, 1, At, B1); PG8_BAR; PG8_SCHED;
;             PG8_LDA(At, 0, 1); PG8_STAGE(PG8_SB(0, 0), b2); PG8_STAGE(PG8_SB(0, 1), b2 + hstep); PG8_STAGE(PG8_SA(0, 0), a2);
;             PG8_WAIT_V(8); PG8_WAIT_L(0); PG8_BAR; PG8_MMA(1, 0, At, B0); PG8_MMA(1, 1, At, B1); PG8_BAR; PG8_SCHED;
.LBB0_292:
	s_add_i32 s93, s72, 2
	s_add_u32 s94, s46, 0x80
	s_addc_u32 s73, s47, 0
	s_add_i32 vcc_lo, 0, 0x10000
	s_cmp_eq_u32 s90, s72
	s_cselect_b32 s72, s68, s94
	s_cselect_b32 s94, 0, s70
	s_cselect_b32 s73, s69, s73
	s_cselect_b32 s95, 0, s71
	s_add_u32 s94, s14, s94
	s_addc_u32 s95, s15, s95
	s_add_i32 vcc_hi, 0, 0x14000
	v_add_u32_e32 v142, vcc_lo, v223
	v_add_u32_e32 v192, vcc_hi, v223
	ds_read_b128 v[130:133], v142
	ds_read_b128 v[134:137], v142 offset:1024
	ds_read_b128 v[138:141], v142 offset:2048
	ds_read_b128 v[142:145], v142 offset:3072
	ds_read_b128 v[180:183], v192
	ds_read_b128 v[184:187], v192 offset:1024
	ds_read_b128 v[188:191], v192 offset:2048
	ds_read_b128 v[192:195], v192 offset:3072
	v_lshl_add_u64 v[242:243], s[46:47], 0, v[176:177]
	s_add_i32 m0, s41, 0xc000
	ds_read_b128 v[196:199], v224
	ds_read_b128 v[200:203], v224 offset:1024
	ds_read_b128 v[204:207], v224 offset:2048
	ds_read_b128 v[208:211], v224 offset:3072
	ds_read_b128 v[226:229], v224 offset:4096
	ds_read_b128 v[230:233], v224 offset:5120
	ds_read_b128 v[234:237], v224 offset:6144
	ds_read_b128 v[238:241], v224 offset:7168
	global_load_lds_dwordx4 v[242:243], off
	v_lshl_add_u64 v[242:243], s[46:47], 0, v[178:179]
	s_add_i32 m0, s41, 0xe000
	s_nop 0
	global_load_lds_dwordx4 v[242:243], off
	s_waitcnt vmcnt(8)
	s_waitcnt lgkmcnt(0)
	s_barrier
	s_setprio 1
	s_waitcnt lgkmcnt(0)
	v_mfma_f32_16x16x32_bf16 v[2:5], v[130:133], v[196:199], v[2:5]
	v_mfma_f32_16x16x32_bf16 v[6:9], v[138:141], v[196:199], v[6:9]
	v_mfma_f32_16x16x32_bf16 v[18:21], v[130:133], v[204:207], v[18:21]
	v_mfma_f32_16x16x32_bf16 v[26:29], v[138:141], v[204:207], v[26:29]
	v_mfma_f32_16x16x32_bf16 v[34:37], v[130:133], v[226:229], v[34:37]
	v_mfma_f32_16x16x32_bf16 v[42:45], v[138:141], v[226:229], v[42:45]
	v_mfma_f32_16x16x32_bf16 v[50:53], v[130:133], v[234:237], v[50:53]
	v_mfma_f32_16x16x32_bf16 v[58:61], v[138:141], v[234:237], v[58:61]
	s_setprio 0
	s_setprio 1
	v_mfma_f32_16x16x32_bf16 v[2:5], v[134:137], v[200:203], v[2:5]
	v_mfma_f32_16x16x32_bf16 v[6:9], v[142:145], v[200:203], v[6:9]
	v_mfma_f32_16x16x32_bf16 v[18:21], v[134:137], v[208:211], v[18:21]
	v_mfma_f32_16x16x32_bf16 v[26:29], v[142:145], v[208:211], v[26:29]
	v_mfma_f32_16x16x32_bf16 v[34:37], v[134:137], v[230:233], v[34:37]
	v_mfma_f32_16x16x32_bf16 v[42:45], v[142:145], v[230:233], v[42:45]
	v_mfma_f32_16x16x32_bf16 v[50:53], v[134:137], v[238:241], v[50:53]
	v_mfma_f32_16x16x32_bf16 v[58:61], v[142:145], v[238:241], v[58:61]
	s_setprio 0
	s_setprio 1
	v_mfma_f32_16x16x32_bf16 v[10:13], v[180:183], v[196:199], v[10:13]
	v_mfma_f32_16x16x32_bf16 v[14:17], v[188:191], v[196:199], v[14:17]
	v_mfma_f32_16x16x32_bf16 v[22:25], v[180:183], v[204:207], v[22:25]
	v_mfma_f32_16x16x32_bf16 v[30:33], v[188:191], v[204:207], v[30:33]
	v_mfma_f32_16x16x32_bf16 v[38:41], v[180:183], v[226:229], v[38:41]
	v_mfma_f32_16x16x32_bf16 v[46:49], v[188:191], v[226:229], v[46:49]
	v_mfma_f32_16x16x32_bf16 v[54:57], v[180:183], v[234:237], v[54:57]
	v_mfma_f32_16x16x32_bf16 v[62:65], v[188:191], v[234:237], v[62:65]
	s_setprio 0
	s_setprio 1
	v_mfma_f32_16x16x32_bf16 v[10:13], v[184:187], v[200:203], v[10:13]
	v_mfma_f32_16x16x32_bf16 v[14:17], v[192:195], v[200:203], v[14:17]
	v_mfma_f32_16x16x32_bf16 v[22:25], v[184:187], v[208:211], v[22:25]
	v_mfma_f32_16x16x32_bf16 v[30:33], v[192:195], v[208:211], v[30:33]
	v_mfma_f32_16x16x32_bf16 v[38:41], v[184:187], v[230:233], v[38:41]
	v_mfma_f32_16x16x32_bf16 v[46:49], v[192:195], v[230:233], v[46:49]
	v_mfma_f32_16x16x32_bf16 v[54:57], v[184:187], v[238:241], v[54:57]
	v_mfma_f32_16x16x32_bf16 v[62:65], v[192:195], v[238:241], v[62:65]
	s_setprio 0
	s_barrier
	s_add_i32 vcc_lo, vcc_lo, s56
	v_lshl_add_u64 v[242:243], s[94:95], 0, v[0:1]
	s_mov_b32 m0, vcc_lo
	ds_read_b128 v[196:199], v224 offset:16384
	ds_read_b128 v[200:203], v224 offset:17408
	ds_read_b128 v[204:207], v224 offset:18432
	ds_read_b128 v[208:211], v224 offset:19456
	ds_read_b128 v[226:229], v224 offset:20480
	ds_read_b128 v[230:233], v224 offset:21504
	ds_read_b128 v[234:237], v224 offset:22528
	ds_read_b128 v[238:241], v224 offset:23552
	global_load_lds_dwordx4 v[242:243], off
	s_add_i32 m0, vcc_lo, 0x2000
	v_lshl_add_u64 v[244:245], s[94:95], 0, v[164:165]
	s_add_u32 s94, s94, s36
	s_addc_u32 s95, s95, 0
	s_add_i32 vcc_lo, vcc_hi, s56
	global_load_lds_dwordx4 v[244:245], off
	v_lshl_add_u64 v[246:247], s[94:95], 0, v[0:1]
	s_mov_b32 m0, vcc_lo
	v_lshl_add_u64 v[248:249], s[94:95], 0, v[164:165]
	global_load_lds_dwordx4 v[246:247], off
	s_add_i32 m0, vcc_lo, 0x2000
	v_lshl_add_u64 v[250:251], s[72:73], 0, v[0:1]
	global_load_lds_dwordx4 v[248:249], off
	s_mov_b32 m0, s41
	v_lshl_add_u64 v[252:253], s[72:73], 0, v[164:165]
	global_load_lds_dwordx4 v[250:251], off
	s_mov_b32 m0, s52
	s_nop 0
	global_load_lds_dwordx4 v[252:253], off
	s_waitcnt vmcnt(8)
	s_waitcnt lgkmcnt(0)
	s_barrier
; #define PG8_STAGE(bufoff, gbase) do { _Pragma("unroll") for (int _i = 0; _i < 2; ++_i) \
;         __builtin_amdgcn_global_load_lds((const unsigned*)((const char*)(gbase) + voffA[_i]), (LAS unsigned*)(lds + (bufoff) + ldsw + _i * 8192), 16, 0, 0); } while (0)
; #define PG8_LDA(dst, b, h) do { _Pragma("unroll") for (int m = 0; m < 4; ++m) _Pragma("unroll") for (int k = 0; k < 2; ++k) dst[m][k] = *(const LAS bf16x8*)(lds + PG8_SA(b, h) + aoff + m * 2048 + k * 1024); } while (0)
; #define PG8_LDB(dst, b, h) do { _Pragma("unroll") for (int n = 0; n < 2; ++n) _Pragma("unroll") for (int k = 0; k < 2; ++k) dst[n][k] = *(const LAS bf16x8*)(lds + PG8_SB(b, h) + boff + n * 2048 + k * 1024); } while (0)
; #define PG8_MMA(ai, bj, At, Bt) do { __builtin_amdgcn_s_setprio(1); _Pragma("unroll") for (int m = 0; m < 4; ++m) _Pragma("unroll") for (int n = 0; n < 2; ++n) _Pragma("unroll") for (int k = 0; k < 2; ++k) \
;         acc[ai][bj][m][n] = __builtin_amdgcn_mfma_f32_16x16x32_bf16(Bt[n][k], At[m][k], acc[ai][bj][m][n], 0, 0, 0); __builtin_amdgcn_s_setprio(0); } while (0)
; #define PG8_WAIT_V(n) asm volatile("s_waitcnt vmcnt(" #n ")" ::: "memory")
; #define PG8_WAIT_L(n) asm volatile("s_waitcnt lgkmcnt(" #n ")" ::: "memory")
; #define PG8_BAR __builtin_amdgcn_s_barrier()
; #define PG8_SCHED __builtin_amdgcn_sched_barrier(0)
; template <class Epi, class Sched>
; __device__ __forceinline__ void gemm_phase(LAS unsigned char* lds, const Gemm g, const Sched& S, const Epi& E) {
;     ...
;             PG8_WAIT_V(8); PG8_WAIT_L(0); PG8_BAR; PG8_MMA(1, 0, At, B0); PG8_MMA(1, 1, At, B1); PG8_BAR; PG8_SCHED;
;             PG8_LDB(B0, 1, 0); PG8_LDB(B1, 1, 1); PG8_SCHED; PG8_LDA(At, 1, 0); PG8_STAGE(PG8_SA(0, 1), a2 + hstep);
;             PG8_WAIT_V(8); PG8_WAIT_L(0); PG8_BAR; PG8_MMA(0, 0, At, B0); PG8_MMA(0, 1, At, B1); PG8_BAR; PG8_SCHED;
	s_setprio 1
	s_waitcnt lgkmcnt(0)
	v_mfma_f32_16x16x32_bf16 v[66:69], v[130:133], v[196:199], v[66:69]
	v_mfma_f32_16x16x32_bf16 v[74:77], v[138:141], v[196:199], v[74:77]
	v_mfma_f32_16x16x32_bf16 v[82:85], v[130:133], v[204:207], v[82:85]
	v_mfma_f32_16x16x32_bf16 v[90:93], v[138:141], v[204:207], v[90:93]
	v_mfma_f32_16x16x32_bf16 v[98:101], v[130:133], v[226:229], v[98:101]
	v_mfma_f32_16x16x32_bf16 v[106:109], v[138:141], v[226:229], v[106:109]
	v_mfma_f32_16x16x32_bf16 v[114:117], v[130:133], v[234:237], v[114:117]
	v_mfma_f32_16x16x32_bf16 v[122:125], v[138:141], v[234:237], v[122:125]
	s_setprio 0
	s_setprio 1
	v_mfma_f32_16x16x32_bf16 v[66:69], v[134:137], v[200:203], v[66:69]
	v_mfma_f32_16x16x32_bf16 v[74:77], v[142:145], v[200:203], v[74:77]
	v_mfma_f32_16x16x32_bf16 v[82:85], v[134:137], v[208:211], v[82:85]
	v_mfma_f32_16x16x32_bf16 v[90:93], v[142:145], v[208:211], v[90:93]
	v_mfma_f32_16x16x32_bf16 v[98:101], v[134:137], v[230:233], v[98:101]
	v_mfma_f32_16x16x32_bf16 v[106:109], v[142:145], v[230:233], v[106:109]
	v_mfma_f32_16x16x32_bf16 v[114:117], v[134:137], v[238:241], v[114:117]
	v_mfma_f32_16x16x32_bf16 v[122:125], v[142:145], v[238:241], v[122:125]
	s_setprio 0
	s_setprio 1
	v_mfma_f32_16x16x32_bf16 v[70:73], v[180:183], v[196:199], v[70:73]
	v_mfma_f32_16x16x32_bf16 v[78:81], v[188:191], v[196:199], v[78:81]
	v_mfma_f32_16x16x32_bf16 v[86:89], v[180:183], v[204:207], v[86:89]
	v_mfma_f32_16x16x32_bf16 v[94:97], v[188:191], v[204:207], v[94:97]
	v_mfma_f32_16x16x32_bf16 v[102:105], v[180:183], v[226:229], v[102:105]
	v_mfma_f32_16x16x32_bf16 v[110:113], v[188:191], v[226:229], v[110:113]
	v_mfma_f32_16x16x32_bf16 v[118:121], v[180:183], v[234:237], v[118:121]
	v_mfma_f32_16x16x32_bf16 v[126:129], v[188:191], v[234:237], v[126:129]
	s_setprio 0
	s_setprio 1
	v_mfma_f32_16x16x32_bf16 v[70:73], v[184:187], v[200:203], v[70:73]
	v_mfma_f32_16x16x32_bf16 v[78:81], v[192:195], v[200:203], v[78:81]
	v_mfma_f32_16x16x32_bf16 v[86:89], v[184:187], v[208:211], v[86:89]
	v_mfma_f32_16x16x32_bf16 v[94:97], v[192:195], v[208:211], v[94:97]
	v_mfma_f32_16x16x32_bf16 v[102:105], v[184:187], v[230:233], v[102:105]
	v_mfma_f32_16x16x32_bf16 v[110:113], v[192:195], v[230:233], v[110:113]
	v_mfma_f32_16x16x32_bf16 v[118:121], v[184:187], v[238:241], v[118:121]
	v_mfma_f32_16x16x32_bf16 v[126:129], v[192:195], v[238:241], v[126:129]
	s_setprio 0
	s_barrier
	s_add_i32 s94, 0, 0x1c000
	v_add_u32_e32 v142, s99, v223
	v_add_u32_e32 v192, s94, v223
	ds_read_b128 v[130:133], v142
	ds_read_b128 v[134:137], v142 offset:1024
	ds_read_b128 v[138:141], v142 offset:2048
	ds_read_b128 v[142:145], v142 offset:3072
	ds_read_b128 v[180:183], v192
	ds_read_b128 v[184:187], v192 offset:1024
	ds_read_b128 v[188:191], v192 offset:2048
	ds_read_b128 v[192:195], v192 offset:3072
	s_add_u32 s72, s72, s36
	s_addc_u32 s73, s73, 0
	s_mov_b32 m0, s33
	v_lshl_add_u64 v[216:217], s[72:73], 0, v[0:1]
	ds_read_b128 v[196:199], v224 offset:32768
	ds_read_b128 v[200:203], v224 offset:33792
	ds_read_b128 v[204:207], v224 offset:34816
	ds_read_b128 v[208:211], v224 offset:35840
	ds_read_b128 v[226:229], v224 offset:36864
	ds_read_b128 v[230:233], v224 offset:37888
	ds_read_b128 v[234:237], v224 offset:38912
	ds_read_b128 v[238:241], v224 offset:39936
	global_load_lds_dwordx4 v[216:217], off
	v_lshl_add_u64 v[216:217], s[72:73], 0, v[164:165]
	s_mov_b32 m0, s0
	s_nop 0
	global_load_lds_dwordx4 v[216:217], off
	s_waitcnt vmcnt(8)
	s_waitcnt lgkmcnt(0)
	s_barrier
	s_setprio 1
	s_waitcnt lgkmcnt(0)
	v_mfma_f32_16x16x32_bf16 v[2:5], v[130:133], v[196:199], v[2:5]
	v_mfma_f32_16x16x32_bf16 v[6:9], v[138:141], v[196:199], v[6:9]
	v_mfma_f32_16x16x32_bf16 v[18:21], v[130:133], v[204:207], v[18:21]
	v_mfma_f32_16x16x32_bf16 v[26:29], v[138:141], v[204:207], v[26:29]
	v_mfma_f32_16x16x32_bf16 v[34:37], v[130:133], v[226:229], v[34:37]
	v_mfma_f32_16x16x32_bf16 v[42:45], v[138:141], v[226:229], v[42:45]
	v_mfma_f32_16x16x32_bf16 v[50:53], v[130:133], v[234:237], v[50:53]
	v_mfma_f32_16x16x32_bf16 v[58:61], v[138:141], v[234:237], v[58:61]
	s_setprio 0
	s_setprio 1
	v_mfma_f32_16x16x32_bf16 v[2:5], v[134:137], v[200:203], v[2:5]
	v_mfma_f32_16x16x32_bf16 v[6:9], v[142:145], v[200:203], v[6:9]
	v_mfma_f32_16x16x32_bf16 v[18:21], v[134:137], v[208:211], v[18:21]
	v_mfma_f32_16x16x32_bf16 v[26:29], v[142:145], v[208:211], v[26:29]
	v_mfma_f32_16x16x32_bf16 v[34:37], v[134:137], v[230:233], v[34:37]
	v_mfma_f32_16x16x32_bf16 v[42:45], v[142:145], v[230:233], v[42:45]
	v_mfma_f32_16x16x32_bf16 v[50:53], v[134:137], v[238:241], v[50:53]
	v_mfma_f32_16x16x32_bf16 v[58:61], v[142:145], v[238:241], v[58:61]
	s_setprio 0
	s_setprio 1
	v_mfma_f32_16x16x32_bf16 v[10:13], v[180:183], v[196:199], v[10:13]
	v_mfma_f32_16x16x32_bf16 v[14:17], v[188:191], v[196:199], v[14:17]
	v_mfma_f32_16x16x32_bf16 v[22:25], v[180:183], v[204:207], v[22:25]
	v_mfma_f32_16x16x32_bf16 v[30:33], v[188:191], v[204:207], v[30:33]
	v_mfma_f32_16x16x32_bf16 v[38:41], v[180:183], v[226:229], v[38:41]
	v_mfma_f32_16x16x32_bf16 v[46:49], v[188:191], v[226:229], v[46:49]
	v_mfma_f32_16x16x32_bf16 v[54:57], v[180:183], v[234:237], v[54:57]
	v_mfma_f32_16x16x32_bf16 v[62:65], v[188:191], v[234:237], v[62:65]
	s_setprio 0
	s_setprio 1
	v_mfma_f32_16x16x32_bf16 v[10:13], v[184:187], v[200:203], v[10:13]
	v_mfma_f32_16x16x32_bf16 v[14:17], v[192:195], v[200:203], v[14:17]
	v_mfma_f32_16x16x32_bf16 v[22:25], v[184:187], v[208:211], v[22:25]
	v_mfma_f32_16x16x32_bf16 v[30:33], v[192:195], v[208:211], v[30:33]
	v_mfma_f32_16x16x32_bf16 v[38:41], v[184:187], v[230:233], v[38:41]
	v_mfma_f32_16x16x32_bf16 v[46:49], v[192:195], v[230:233], v[46:49]
	v_mfma_f32_16x16x32_bf16 v[54:57], v[184:187], v[238:241], v[54:57]
	v_mfma_f32_16x16x32_bf16 v[62:65], v[192:195], v[238:241], v[62:65]
	s_setprio 0
	s_barrier
; #define PG8_STAGE(bufoff, gbase) do { _Pragma("unroll") for (int _i = 0; _i < 2; ++_i) \
;         __builtin_amdgcn_global_load_lds((const unsigned*)((const char*)(gbase) + voffA[_i]), (LAS unsigned*)(lds + (bufoff) + ldsw + _i * 8192), 16, 0, 0); } while (0)
; #define PG8_LDA(dst, b, h) do { _Pragma("unroll") for (int m = 0; m < 4; ++m) _Pragma("unroll") for (int k = 0; k < 2; ++k) dst[m][k] = *(const LAS bf16x8*)(lds + PG8_SA(b, h) + aoff + m * 2048 + k * 1024); } while (0)
; #define PG8_MMA(ai, bj, At, Bt) do { __builtin_amdgcn_s_setprio(1); _Pragma("unroll") for (int m = 0; m < 4; ++m) _Pragma("unroll") for (int n = 0; n < 2; ++n) _Pragma("unroll") for (int k = 0; k < 2; ++k) \
;         acc[ai][bj][m][n] = __builtin_amdgcn_mfma_f32_16x16x32_bf16(Bt[n][k], At[m][k], acc[ai][bj][m][n], 0, 0, 0); __builtin_amdgcn_s_setprio(0); } while (0)
; #define PG8_WAIT_V(n) asm volatile("s_waitcnt vmcnt(" #n ")" ::: "memory")
; #define PG8_WAIT_L(n) asm volatile("s_waitcnt lgkmcnt(" #n ")" ::: "memory")
; #define PG8_BAR __builtin_amdgcn_s_barrier()
; #define PG8_SCHED __builtin_amdgcn_sched_barrier(0)
; template <class Epi, class Sched>
; __device__ __forceinline__ void gemm_phase(LAS unsigned char* lds, const Gemm g, const Sched& S, const Epi& E) {
;     ...
;             PG8_LDA(At, 1, 1); PG8_STAGE(PG8_SB(1, 0), b3); PG8_STAGE(PG8_SB(1, 1), b3 + hstep); PG8_STAGE(PG8_SA(1, 0), a3);
;             PG8_WAIT_V(8); PG8_WAIT_L(0); PG8_BAR; PG8_MMA(1, 0, At, B0); PG8_MMA(1, 1, At, B1); PG8_BAR; PG8_SCHED;
;         }
;         if (wr == 0) PG8_BAR;
	s_add_i32 s72, s99, s56
	v_lshl_add_u64 v[216:217], v[242:243], 0, s[26:27]
	s_mov_b32 m0, s72
	ds_read_b128 v[196:199], v224 offset:49152
	ds_read_b128 v[200:203], v224 offset:50176
	ds_read_b128 v[204:207], v224 offset:51200
	ds_read_b128 v[208:211], v224 offset:52224
	ds_read_b128 v[226:229], v224 offset:53248
	ds_read_b128 v[230:233], v224 offset:54272
	ds_read_b128 v[234:237], v224 offset:55296
	ds_read_b128 v[238:241], v224 offset:56320
	global_load_lds_dwordx4 v[216:217], off
	v_lshl_add_u64 v[216:217], v[244:245], 0, s[26:27]
	s_add_i32 m0, s72, 0x2000
	s_add_i32 s72, s94, s56
	global_load_lds_dwordx4 v[216:217], off
	v_lshl_add_u64 v[216:217], v[246:247], 0, s[26:27]
	s_mov_b32 m0, s72
	s_nop 0
	global_load_lds_dwordx4 v[216:217], off
	v_lshl_add_u64 v[216:217], v[248:249], 0, s[26:27]
	s_add_i32 m0, s72, 0x2000
	s_nop 0
	global_load_lds_dwordx4 v[216:217], off
	v_lshl_add_u64 v[216:217], v[250:251], 0, s[26:27]
	s_mov_b32 m0, s88
	s_nop 0
	global_load_lds_dwordx4 v[216:217], off
	v_lshl_add_u64 v[216:217], v[252:253], 0, s[26:27]
	s_mov_b32 m0, s89
	s_nop 0
	global_load_lds_dwordx4 v[216:217], off
	s_waitcnt vmcnt(8)
	s_waitcnt lgkmcnt(0)
	s_barrier
	s_setprio 1
	s_waitcnt lgkmcnt(0)
	v_mfma_f32_16x16x32_bf16 v[66:69], v[130:133], v[196:199], v[66:69]
	v_mfma_f32_16x16x32_bf16 v[74:77], v[138:141], v[196:199], v[74:77]
	v_mfma_f32_16x16x32_bf16 v[82:85], v[130:133], v[204:207], v[82:85]
	v_mfma_f32_16x16x32_bf16 v[90:93], v[138:141], v[204:207], v[90:93]
	v_mfma_f32_16x16x32_bf16 v[98:101], v[130:133], v[226:229], v[98:101]
	v_mfma_f32_16x16x32_bf16 v[106:109], v[138:141], v[226:229], v[106:109]
	v_mfma_f32_16x16x32_bf16 v[114:117], v[130:133], v[234:237], v[114:117]
	v_mfma_f32_16x16x32_bf16 v[122:125], v[138:141], v[234:237], v[122:125]
	s_setprio 0
	s_setprio 1
	v_mfma_f32_16x16x32_bf16 v[66:69], v[134:137], v[200:203], v[66:69]
	v_mfma_f32_16x16x32_bf16 v[74:77], v[142:145], v[200:203], v[74:77]
	v_mfma_f32_16x16x32_bf16 v[82:85], v[134:137], v[208:211], v[82:85]
	v_mfma_f32_16x16x32_bf16 v[90:93], v[142:145], v[208:211], v[90:93]
	v_mfma_f32_16x16x32_bf16 v[98:101], v[134:137], v[230:233], v[98:101]
	v_mfma_f32_16x16x32_bf16 v[106:109], v[142:145], v[230:233], v[106:109]
	v_mfma_f32_16x16x32_bf16 v[114:117], v[134:137], v[238:241], v[114:117]
	v_mfma_f32_16x16x32_bf16 v[122:125], v[142:145], v[238:241], v[122:125]
	s_setprio 0
	s_setprio 1
	v_mfma_f32_16x16x32_bf16 v[70:73], v[180:183], v[196:199], v[70:73]
	v_mfma_f32_16x16x32_bf16 v[78:81], v[188:191], v[196:199], v[78:81]
	v_mfma_f32_16x16x32_bf16 v[86:89], v[180:183], v[204:207], v[86:89]
	v_mfma_f32_16x16x32_bf16 v[94:97], v[188:191], v[204:207], v[94:97]
	v_mfma_f32_16x16x32_bf16 v[102:105], v[180:183], v[226:229], v[102:105]
	v_mfma_f32_16x16x32_bf16 v[110:113], v[188:191], v[226:229], v[110:113]
	v_mfma_f32_16x16x32_bf16 v[118:121], v[180:183], v[234:237], v[118:121]
	v_mfma_f32_16x16x32_bf16 v[126:129], v[188:191], v[234:237], v[126:129]
	s_setprio 0
	s_setprio 1
	v_mfma_f32_16x16x32_bf16 v[70:73], v[184:187], v[200:203], v[70:73]
	v_mfma_f32_16x16x32_bf16 v[78:81], v[192:195], v[200:203], v[78:81]
	v_mfma_f32_16x16x32_bf16 v[86:89], v[184:187], v[208:211], v[86:89]
	v_mfma_f32_16x16x32_bf16 v[94:97], v[192:195], v[208:211], v[94:97]
	v_mfma_f32_16x16x32_bf16 v[102:105], v[184:187], v[230:233], v[102:105]
	v_mfma_f32_16x16x32_bf16 v[110:113], v[192:195], v[230:233], v[110:113]
	v_mfma_f32_16x16x32_bf16 v[118:121], v[184:187], v[238:241], v[118:121]
	v_mfma_f32_16x16x32_bf16 v[126:129], v[192:195], v[238:241], v[126:129]
	s_setprio 0
	s_barrier
	s_add_u32 s46, s46, 0x100
	s_addc_u32 s47, s47, 0
	s_add_u32 s70, s70, 0x100
	s_addc_u32 s71, s71, 0
	s_cmp_ge_u32 s93, s1
	s_mov_b32 s72, s93
	s_cbranch_scc0 .LBB0_292
	s_and_b64 vcc, exec, s[60:61]
	s_cbranch_vccz .LBB0_295
	s_barrier

; #define PG8_STAGE(bufoff, gbase) do { _Pragma("unroll") for (int _i = 0; _i < 2; ++_i) \
;         __builtin_amdgcn_global_load_lds((const unsigned*)((const char*)(gbase) + voffA[_i]), (LAS unsigned*)(lds + (bufoff) + ldsw + _i * 8192), 16, 0, 0); } while (0)
; #define PG8_LDA(dst, b, h) do { _Pragma("unroll") for (int m = 0; m < 4; ++m) _Pragma("unroll") for (int k = 0; k < 2; ++k) dst[m][k] = *(const LAS bf16x8*)(lds + PG8_SA(b, h) + aoff + m * 2048 + k * 1024); } while (0)
; #define PG8_LDB(dst, b, h) do { _Pragma("unroll") for (int n = 0; n < 2; ++n) _Pragma("unroll") for (int k = 0; k < 2; ++k) dst[n][k] = *(const LAS bf16x8*)(lds + PG8_SB(b, h) + boff + n * 2048 + k * 1024); } while (0)
; #define PG8_MMA(ai, bj, At, Bt) do { __builtin_amdgcn_s_setprio(1); _Pragma("unroll") for (int m = 0; m < 4; ++m) _Pragma("unroll") for (int n = 0; n < 2; ++n) _Pragma("unroll") for (int k = 0; k < 2; ++k) \
;         acc[ai][bj][m][n] = __builtin_amdgcn_mfma_f32_16x16x32_bf16(Bt[n][k], At[m][k], acc[ai][bj][m][n], 0, 0, 0); __builtin_amdgcn_s_setprio(0); } while (0)
; #define PG8_WAIT_V(n) asm volatile("s_waitcnt vmcnt(" #n ")" ::: "memory")
; #define PG8_WAIT_L(n) asm volatile("s_waitcnt lgkmcnt(" #n ")" ::: "memory")
; #define PG8_BAR __builtin_amdgcn_s_barrier()
; #define PG8_SCHED __builtin_amdgcn_sched_barrier(0)
; template <class Epi, class Sched>
; __device__ __forceinline__ void gemm_phase(LAS unsigned char* lds, const Gemm g, const Sched& S, const Epi& E) {
;     ...
;         for (int t = 0; t < nt; t += 2) {
;             const bool last = (t == nt - 2);
;             const char* a1 = cA + (size_t)(t + 1) * kstep;
;             const char* a2 = last ? nA : cA + (size_t)(t + 2) * kstep; const char* b2 = last ? nB : cB + (size_t)(t + 2) * kstep;
;             const char* a3 = a2 + kstep; const char* b3 = b2 + kstep;
;             PG8_LDB(B0, 0, 0); PG8_LDB(B1, 0, 1); PG8_SCHED; PG8_LDA(At, 0, 0); PG8_STAGE(PG8_SA(1, 1), a1 + hstep);
;             PG8_WAIT_V(8); PG8_WAIT_L(0); PG8_BAR; PG8_MMA(0, 0, At, B0); PG8_MMA(0, 1, At, B1); PG8_BAR; PG8_SCHED;
;             PG8_LDA(At, 0, 1); PG8_STAGE(PG8_SB(0, 0), b2); PG8_STAGE(PG8_SB(0, 1), b2 + hstep); PG8_STAGE(PG8_SA(0, 0), a2);
;             PG8_WAIT_V(8); PG8_WAIT_L(0); PG8_BAR; PG8_MMA(1, 0, At, B0); PG8_MMA(1, 1, At, B1); PG8_BAR; PG8_SCHED;
.LBB0_339:
	s_add_u32 s62, s44, 0x100
	s_addc_u32 s63, s45, 0
	s_add_i32 s88, 0, 0x10000
	s_cmpk_eq_i32 s85, 0x52
	s_cselect_b32 s67, s47, s63
	s_cselect_b32 s66, s46, s62
	s_cselect_b32 s65, s15, s84
	s_cselect_b32 s64, s14, s75
	s_add_i32 s89, 0, 0x14000
	v_add_u32_e32 v142, s88, v209
	v_add_u32_e32 v188, s89, v209
	ds_read_b128 v[130:133], v142
	ds_read_b128 v[134:137], v142 offset:1024
	ds_read_b128 v[138:141], v142 offset:2048
	ds_read_b128 v[142:145], v142 offset:3072
	ds_read_b128 v[176:179], v188
	ds_read_b128 v[180:183], v188 offset:1024
	ds_read_b128 v[184:187], v188 offset:2048
	ds_read_b128 v[188:191], v188 offset:3072
	v_lshl_add_u64 v[238:239], s[44:45], 0, v[172:173]
	s_add_i32 m0, s2, 0xc000
	ds_read_b128 v[192:195], v210
	ds_read_b128 v[196:199], v210 offset:1024
	ds_read_b128 v[200:203], v210 offset:2048
	ds_read_b128 v[204:207], v210 offset:3072
	ds_read_b128 v[222:225], v210 offset:4096
	ds_read_b128 v[226:229], v210 offset:5120
	ds_read_b128 v[230:233], v210 offset:6144
	ds_read_b128 v[234:237], v210 offset:7168
	global_load_lds_dwordx4 v[238:239], off
	v_lshl_add_u64 v[238:239], s[44:45], 0, v[174:175]
	s_add_i32 m0, s2, 0xe000
	s_nop 0
	global_load_lds_dwordx4 v[238:239], off
	s_waitcnt vmcnt(8)
	s_waitcnt lgkmcnt(0)
	s_barrier
	s_setprio 1
	s_waitcnt lgkmcnt(0)
	v_mfma_f32_16x16x32_bf16 v[126:129], v[130:133], v[192:195], v[126:129]
	v_mfma_f32_16x16x32_bf16 v[122:125], v[138:141], v[192:195], v[122:125]
	v_mfma_f32_16x16x32_bf16 v[110:113], v[130:133], v[200:203], v[110:113]
	v_mfma_f32_16x16x32_bf16 v[106:109], v[138:141], v[200:203], v[106:109]
	v_mfma_f32_16x16x32_bf16 v[94:97], v[130:133], v[222:225], v[94:97]
	v_mfma_f32_16x16x32_bf16 v[90:93], v[138:141], v[222:225], v[90:93]
	v_mfma_f32_16x16x32_bf16 v[78:81], v[130:133], v[230:233], v[78:81]
	v_mfma_f32_16x16x32_bf16 v[74:77], v[138:141], v[230:233], v[74:77]
	s_setprio 0
	s_setprio 1
	v_mfma_f32_16x16x32_bf16 v[126:129], v[134:137], v[196:199], v[126:129]
	v_mfma_f32_16x16x32_bf16 v[122:125], v[142:145], v[196:199], v[122:125]
	v_mfma_f32_16x16x32_bf16 v[110:113], v[134:137], v[204:207], v[110:113]
	v_mfma_f32_16x16x32_bf16 v[106:109], v[142:145], v[204:207], v[106:109]
	v_mfma_f32_16x16x32_bf16 v[94:97], v[134:137], v[226:229], v[94:97]
	v_mfma_f32_16x16x32_bf16 v[90:93], v[142:145], v[226:229], v[90:93]
	v_mfma_f32_16x16x32_bf16 v[78:81], v[134:137], v[234:237], v[78:81]
	v_mfma_f32_16x16x32_bf16 v[74:77], v[142:145], v[234:237], v[74:77]
	s_setprio 0
	s_setprio 1
	v_mfma_f32_16x16x32_bf16 v[118:121], v[176:179], v[192:195], v[118:121]
	v_mfma_f32_16x16x32_bf16 v[114:117], v[184:187], v[192:195], v[114:117]
	v_mfma_f32_16x16x32_bf16 v[102:105], v[176:179], v[200:203], v[102:105]
	v_mfma_f32_16x16x32_bf16 v[98:101], v[184:187], v[200:203], v[98:101]
	v_mfma_f32_16x16x32_bf16 v[86:89], v[176:179], v[222:225], v[86:89]
	v_mfma_f32_16x16x32_bf16 v[82:85], v[184:187], v[222:225], v[82:85]
	v_mfma_f32_16x16x32_bf16 v[70:73], v[176:179], v[230:233], v[70:73]
	v_mfma_f32_16x16x32_bf16 v[66:69], v[184:187], v[230:233], v[66:69]
	s_setprio 0
	s_setprio 1
	v_mfma_f32_16x16x32_bf16 v[118:121], v[180:183], v[196:199], v[118:121]
	v_mfma_f32_16x16x32_bf16 v[114:117], v[188:191], v[196:199], v[114:117]
	v_mfma_f32_16x16x32_bf16 v[102:105], v[180:183], v[204:207], v[102:105]
	v_mfma_f32_16x16x32_bf16 v[98:101], v[188:191], v[204:207], v[98:101]
	v_mfma_f32_16x16x32_bf16 v[86:89], v[180:183], v[226:229], v[86:89]
	v_mfma_f32_16x16x32_bf16 v[82:85], v[188:191], v[226:229], v[82:85]
	v_mfma_f32_16x16x32_bf16 v[70:73], v[180:183], v[234:237], v[70:73]
	v_mfma_f32_16x16x32_bf16 v[66:69], v[188:191], v[234:237], v[66:69]
	s_setprio 0
	s_barrier
	s_add_i32 s44, s88, s33
	v_lshl_add_u64 v[238:239], s[64:65], 0, v[0:1]
	s_mov_b32 m0, s44
	ds_read_b128 v[192:195], v210 offset:16384
	ds_read_b128 v[196:199], v210 offset:17408
	ds_read_b128 v[200:203], v210 offset:18432
	ds_read_b128 v[204:207], v210 offset:19456
	ds_read_b128 v[222:225], v210 offset:20480
	ds_read_b128 v[226:229], v210 offset:21504
	ds_read_b128 v[230:233], v210 offset:22528
	ds_read_b128 v[234:237], v210 offset:23552
	global_load_lds_dwordx4 v[238:239], off
	s_add_i32 m0, s44, 0x2000
	s_add_u32 s44, s64, 0x158000
	v_lshl_add_u64 v[240:241], s[64:65], 0, v[164:165]
	s_addc_u32 s45, s65, 0
	s_add_i32 s88, s89, s33
	global_load_lds_dwordx4 v[240:241], off
	v_lshl_add_u64 v[242:243], s[44:45], 0, v[0:1]
	s_mov_b32 m0, s88
	v_lshl_add_u64 v[244:245], s[66:67], 0, v[164:165]
	global_load_lds_dwordx4 v[242:243], off
	v_lshl_add_u64 v[242:243], s[44:45], 0, v[164:165]
	s_add_i32 m0, s88, 0x2000
	s_nop 0
	global_load_lds_dwordx4 v[242:243], off
	v_lshl_add_u64 v[242:243], s[66:67], 0, v[0:1]
	s_mov_b32 m0, s2
	s_nop 0
	global_load_lds_dwordx4 v[242:243], off
	s_mov_b32 m0, s36
	s_nop 0
	global_load_lds_dwordx4 v[244:245], off
	s_waitcnt vmcnt(8)
	s_waitcnt lgkmcnt(0)
	s_barrier
; #define PG8_STAGE(bufoff, gbase) do { _Pragma("unroll") for (int _i = 0; _i < 2; ++_i) \
;         __builtin_amdgcn_global_load_lds((const unsigned*)((const char*)(gbase) + voffA[_i]), (LAS unsigned*)(lds + (bufoff) + ldsw + _i * 8192), 16, 0, 0); } while (0)
; #define PG8_LDA(dst, b, h) do { _Pragma("unroll") for (int m = 0; m < 4; ++m) _Pragma("unroll") for (int k = 0; k < 2; ++k) dst[m][k] = *(const LAS bf16x8*)(lds + PG8_SA(b, h) + aoff + m * 2048 + k * 1024); } while (0)
; #define PG8_LDB(dst, b, h) do { _Pragma("unroll") for (int n = 0; n < 2; ++n) _Pragma("unroll") for (int k = 0; k < 2; ++k) dst[n][k] = *(const LAS bf16x8*)(lds + PG8_SB(b, h) + boff + n * 2048 + k * 1024); } while (0)
; #define PG8_MMA(ai, bj, At, Bt) do { __builtin_amdgcn_s_setprio(1); _Pragma("unroll") for (int m = 0; m < 4; ++m) _Pragma("unroll") for (int n = 0; n < 2; ++n) _Pragma("unroll") for (int k = 0; k < 2; ++k) \
;         acc[ai][bj][m][n] = __builtin_amdgcn_mfma_f32_16x16x32_bf16(Bt[n][k], At[m][k], acc[ai][bj][m][n], 0, 0, 0); __builtin_amdgcn_s_setprio(0); } while (0)
; #define PG8_WAIT_V(n) asm volatile("s_waitcnt vmcnt(" #n ")" ::: "memory")
; #define PG8_WAIT_L(n) asm volatile("s_waitcnt lgkmcnt(" #n ")" ::: "memory")
; #define PG8_BAR __builtin_amdgcn_s_barrier()
; #define PG8_SCHED __builtin_amdgcn_sched_barrier(0)
; template <class Epi, class Sched>
; __device__ __forceinline__ void gemm_phase(LAS unsigned char* lds, const Gemm g, const Sched& S, const Epi& E) {
;     ...
;             PG8_WAIT_V(8); PG8_WAIT_L(0); PG8_BAR; PG8_MMA(1, 0, At, B0); PG8_MMA(1, 1, At, B1); PG8_BAR; PG8_SCHED;
;             PG8_LDB(B0, 1, 0); PG8_LDB(B1, 1, 1); PG8_SCHED; PG8_LDA(At, 1, 0); PG8_STAGE(PG8_SA(0, 1), a2 + hstep);
;             PG8_WAIT_V(8); PG8_WAIT_L(0); PG8_BAR; PG8_MMA(0, 0, At, B0); PG8_MMA(0, 1, At, B1); PG8_BAR; PG8_SCHED;
	s_setprio 1
	s_waitcnt lgkmcnt(0)
	v_mfma_f32_16x16x32_bf16 v[62:65], v[130:133], v[192:195], v[62:65]
	v_mfma_f32_16x16x32_bf16 v[58:61], v[138:141], v[192:195], v[58:61]
	v_mfma_f32_16x16x32_bf16 v[46:49], v[130:133], v[200:203], v[46:49]
	v_mfma_f32_16x16x32_bf16 v[42:45], v[138:141], v[200:203], v[42:45]
	v_mfma_f32_16x16x32_bf16 v[30:33], v[130:133], v[222:225], v[30:33]
	v_mfma_f32_16x16x32_bf16 v[26:29], v[138:141], v[222:225], v[26:29]
	v_mfma_f32_16x16x32_bf16 v[14:17], v[130:133], v[230:233], v[14:17]
	v_mfma_f32_16x16x32_bf16 v[10:13], v[138:141], v[230:233], v[10:13]
	s_setprio 0
	s_setprio 1
	v_mfma_f32_16x16x32_bf16 v[62:65], v[134:137], v[196:199], v[62:65]
	v_mfma_f32_16x16x32_bf16 v[58:61], v[142:145], v[196:199], v[58:61]
	v_mfma_f32_16x16x32_bf16 v[46:49], v[134:137], v[204:207], v[46:49]
	v_mfma_f32_16x16x32_bf16 v[42:45], v[142:145], v[204:207], v[42:45]
	v_mfma_f32_16x16x32_bf16 v[30:33], v[134:137], v[226:229], v[30:33]
	v_mfma_f32_16x16x32_bf16 v[26:29], v[142:145], v[226:229], v[26:29]
	v_mfma_f32_16x16x32_bf16 v[14:17], v[134:137], v[234:237], v[14:17]
	v_mfma_f32_16x16x32_bf16 v[10:13], v[142:145], v[234:237], v[10:13]
	s_setprio 0
	s_setprio 1
	v_mfma_f32_16x16x32_bf16 v[54:57], v[176:179], v[192:195], v[54:57]
	v_mfma_f32_16x16x32_bf16 v[50:53], v[184:187], v[192:195], v[50:53]
	v_mfma_f32_16x16x32_bf16 v[38:41], v[176:179], v[200:203], v[38:41]
	v_mfma_f32_16x16x32_bf16 v[34:37], v[184:187], v[200:203], v[34:37]
	v_mfma_f32_16x16x32_bf16 v[22:25], v[176:179], v[222:225], v[22:25]
	v_mfma_f32_16x16x32_bf16 v[18:21], v[184:187], v[222:225], v[18:21]
	v_mfma_f32_16x16x32_bf16 v[6:9], v[176:179], v[230:233], v[6:9]
	v_mfma_f32_16x16x32_bf16 v[2:5], v[184:187], v[230:233], v[2:5]
	s_setprio 0
	s_setprio 1
	v_mfma_f32_16x16x32_bf16 v[54:57], v[180:183], v[196:199], v[54:57]
	v_mfma_f32_16x16x32_bf16 v[50:53], v[188:191], v[196:199], v[50:53]
	v_mfma_f32_16x16x32_bf16 v[38:41], v[180:183], v[204:207], v[38:41]
	v_mfma_f32_16x16x32_bf16 v[34:37], v[188:191], v[204:207], v[34:37]
	v_mfma_f32_16x16x32_bf16 v[22:25], v[180:183], v[226:229], v[22:25]
	v_mfma_f32_16x16x32_bf16 v[18:21], v[188:191], v[226:229], v[18:21]
	v_mfma_f32_16x16x32_bf16 v[6:9], v[180:183], v[234:237], v[6:9]
	v_mfma_f32_16x16x32_bf16 v[2:5], v[188:191], v[234:237], v[2:5]
	s_setprio 0
	s_barrier
	s_add_i32 s88, 0, 0x1c000
	v_add_u32_e32 v142, s99, v209
	v_add_u32_e32 v188, s88, v209
	ds_read_b128 v[130:133], v142
	ds_read_b128 v[134:137], v142 offset:1024
	ds_read_b128 v[138:141], v142 offset:2048
	ds_read_b128 v[142:145], v142 offset:3072
	ds_read_b128 v[176:179], v188
	ds_read_b128 v[180:183], v188 offset:1024
	ds_read_b128 v[184:187], v188 offset:2048
	ds_read_b128 v[188:191], v188 offset:3072
	s_add_u32 s44, s66, 0x158000
	s_addc_u32 s45, s67, 0
	s_mov_b32 m0, s38
	v_lshl_add_u64 v[246:247], s[44:45], 0, v[0:1]
	ds_read_b128 v[192:195], v210 offset:32768
	ds_read_b128 v[196:199], v210 offset:33792
	ds_read_b128 v[200:203], v210 offset:34816
	ds_read_b128 v[204:207], v210 offset:35840
	ds_read_b128 v[222:225], v210 offset:36864
	ds_read_b128 v[226:229], v210 offset:37888
	ds_read_b128 v[230:233], v210 offset:38912
	ds_read_b128 v[234:237], v210 offset:39936
	global_load_lds_dwordx4 v[246:247], off
	v_lshl_add_u64 v[246:247], s[44:45], 0, v[164:165]
	s_mov_b32 m0, s39
	s_nop 0
	global_load_lds_dwordx4 v[246:247], off
	s_waitcnt vmcnt(8)
	s_waitcnt lgkmcnt(0)
	s_barrier
	s_setprio 1
	s_waitcnt lgkmcnt(0)
	v_mfma_f32_16x16x32_bf16 v[126:129], v[130:133], v[192:195], v[126:129]
	v_mfma_f32_16x16x32_bf16 v[122:125], v[138:141], v[192:195], v[122:125]
	v_mfma_f32_16x16x32_bf16 v[110:113], v[130:133], v[200:203], v[110:113]
	v_mfma_f32_16x16x32_bf16 v[106:109], v[138:141], v[200:203], v[106:109]
	v_mfma_f32_16x16x32_bf16 v[94:97], v[130:133], v[222:225], v[94:97]
	v_mfma_f32_16x16x32_bf16 v[90:93], v[138:141], v[222:225], v[90:93]
	v_mfma_f32_16x16x32_bf16 v[78:81], v[130:133], v[230:233], v[78:81]
	v_mfma_f32_16x16x32_bf16 v[74:77], v[138:141], v[230:233], v[74:77]
	s_setprio 0
	s_setprio 1
	v_mfma_f32_16x16x32_bf16 v[126:129], v[134:137], v[196:199], v[126:129]
	v_mfma_f32_16x16x32_bf16 v[122:125], v[142:145], v[196:199], v[122:125]
	v_mfma_f32_16x16x32_bf16 v[110:113], v[134:137], v[204:207], v[110:113]
	v_mfma_f32_16x16x32_bf16 v[106:109], v[142:145], v[204:207], v[106:109]
	v_mfma_f32_16x16x32_bf16 v[94:97], v[134:137], v[226:229], v[94:97]
	v_mfma_f32_16x16x32_bf16 v[90:93], v[142:145], v[226:229], v[90:93]
	v_mfma_f32_16x16x32_bf16 v[78:81], v[134:137], v[234:237], v[78:81]
	v_mfma_f32_16x16x32_bf16 v[74:77], v[142:145], v[234:237], v[74:77]
	s_setprio 0
	s_setprio 1
	v_mfma_f32_16x16x32_bf16 v[118:121], v[176:179], v[192:195], v[118:121]
	v_mfma_f32_16x16x32_bf16 v[114:117], v[184:187], v[192:195], v[114:117]
	v_mfma_f32_16x16x32_bf16 v[102:105], v[176:179], v[200:203], v[102:105]
	v_mfma_f32_16x16x32_bf16 v[98:101], v[184:187], v[200:203], v[98:101]
	v_mfma_f32_16x16x32_bf16 v[86:89], v[176:179], v[222:225], v[86:89]
	v_mfma_f32_16x16x32_bf16 v[82:85], v[184:187], v[222:225], v[82:85]
	v_mfma_f32_16x16x32_bf16 v[70:73], v[176:179], v[230:233], v[70:73]
	v_mfma_f32_16x16x32_bf16 v[66:69], v[184:187], v[230:233], v[66:69]
	s_setprio 0
	s_setprio 1
	v_mfma_f32_16x16x32_bf16 v[118:121], v[180:183], v[196:199], v[118:121]
	v_mfma_f32_16x16x32_bf16 v[114:117], v[188:191], v[196:199], v[114:117]
	v_mfma_f32_16x16x32_bf16 v[102:105], v[180:183], v[204:207], v[102:105]
	v_mfma_f32_16x16x32_bf16 v[98:101], v[188:191], v[204:207], v[98:101]
	v_mfma_f32_16x16x32_bf16 v[86:89], v[180:183], v[226:229], v[86:89]
	v_mfma_f32_16x16x32_bf16 v[82:85], v[188:191], v[226:229], v[82:85]
	v_mfma_f32_16x16x32_bf16 v[70:73], v[180:183], v[234:237], v[70:73]
	v_mfma_f32_16x16x32_bf16 v[66:69], v[188:191], v[234:237], v[66:69]
	s_setprio 0
	s_barrier
; #define PG8_STAGE(bufoff, gbase) do { _Pragma("unroll") for (int _i = 0; _i < 2; ++_i) \
;         __builtin_amdgcn_global_load_lds((const unsigned*)((const char*)(gbase) + voffA[_i]), (LAS unsigned*)(lds + (bufoff) + ldsw + _i * 8192), 16, 0, 0); } while (0)
; #define PG8_LDA(dst, b, h) do { _Pragma("unroll") for (int m = 0; m < 4; ++m) _Pragma("unroll") for (int k = 0; k < 2; ++k) dst[m][k] = *(const LAS bf16x8*)(lds + PG8_SA(b, h) + aoff + m * 2048 + k * 1024); } while (0)
; #define PG8_MMA(ai, bj, At, Bt) do { __builtin_amdgcn_s_setprio(1); _Pragma("unroll") for (int m = 0; m < 4; ++m) _Pragma("unroll") for (int n = 0; n < 2; ++n) _Pragma("unroll") for (int k = 0; k < 2; ++k) \
;         acc[ai][bj][m][n] = __builtin_amdgcn_mfma_f32_16x16x32_bf16(Bt[n][k], At[m][k], acc[ai][bj][m][n], 0, 0, 0); __builtin_amdgcn_s_setprio(0); } while (0)
; #define PG8_WAIT_V(n) asm volatile("s_waitcnt vmcnt(" #n ")" ::: "memory")
; #define PG8_WAIT_L(n) asm volatile("s_waitcnt lgkmcnt(" #n ")" ::: "memory")
; #define PG8_BAR __builtin_amdgcn_s_barrier()
; #define PG8_SCHED __builtin_amdgcn_sched_barrier(0)
; template <class Epi, class Sched>
; __device__ __forceinline__ void gemm_phase(LAS unsigned char* lds, const Gemm g, const Sched& S, const Epi& E) {
;     ...
;             PG8_LDA(At, 1, 1); PG8_STAGE(PG8_SB(1, 0), b3); PG8_STAGE(PG8_SB(1, 1), b3 + hstep); PG8_STAGE(PG8_SA(1, 0), a3);
;             PG8_WAIT_V(8); PG8_WAIT_L(0); PG8_BAR; PG8_MMA(1, 0, At, B0); PG8_MMA(1, 1, At, B1); PG8_BAR; PG8_SCHED;
;         }
;         if (wr == 0) PG8_BAR;
	s_add_i32 s44, s99, s33
	v_lshl_add_u64 v[238:239], v[238:239], 0, s[26:27]
	s_mov_b32 m0, s44
	ds_read_b128 v[192:195], v210 offset:49152
	ds_read_b128 v[196:199], v210 offset:50176
	ds_read_b128 v[200:203], v210 offset:51200
	ds_read_b128 v[204:207], v210 offset:52224
	ds_read_b128 v[222:225], v210 offset:53248
	ds_read_b128 v[226:229], v210 offset:54272
	ds_read_b128 v[230:233], v210 offset:55296
	ds_read_b128 v[234:237], v210 offset:56320
	global_load_lds_dwordx4 v[238:239], off
	s_add_i32 m0, s44, 0x2000
	s_add_u32 s44, s64, 0x158080
	v_lshl_add_u64 v[238:239], v[240:241], 0, s[26:27]
	s_addc_u32 s45, s65, 0
	s_add_i32 s64, s88, s33
	global_load_lds_dwordx4 v[238:239], off
	v_lshl_add_u64 v[238:239], s[44:45], 0, v[0:1]
	s_mov_b32 m0, s64
	s_nop 0
	global_load_lds_dwordx4 v[238:239], off
	v_lshl_add_u64 v[238:239], s[44:45], 0, v[164:165]
	s_add_i32 m0, s64, 0x2000
	s_nop 0
	global_load_lds_dwordx4 v[238:239], off
	v_lshl_add_u64 v[238:239], v[242:243], 0, s[26:27]
	s_mov_b32 m0, s56
	s_nop 0
	global_load_lds_dwordx4 v[238:239], off
	v_lshl_add_u64 v[238:239], v[244:245], 0, s[26:27]
	s_mov_b32 m0, s68
	s_nop 0
	global_load_lds_dwordx4 v[238:239], off
	s_waitcnt vmcnt(8)
	s_waitcnt lgkmcnt(0)
	s_barrier
	s_setprio 1
	s_waitcnt lgkmcnt(0)
	v_mfma_f32_16x16x32_bf16 v[62:65], v[130:133], v[192:195], v[62:65]
	v_mfma_f32_16x16x32_bf16 v[58:61], v[138:141], v[192:195], v[58:61]
	v_mfma_f32_16x16x32_bf16 v[46:49], v[130:133], v[200:203], v[46:49]
	v_mfma_f32_16x16x32_bf16 v[42:45], v[138:141], v[200:203], v[42:45]
	v_mfma_f32_16x16x32_bf16 v[30:33], v[130:133], v[222:225], v[30:33]
	v_mfma_f32_16x16x32_bf16 v[26:29], v[138:141], v[222:225], v[26:29]
	v_mfma_f32_16x16x32_bf16 v[14:17], v[130:133], v[230:233], v[14:17]
	v_mfma_f32_16x16x32_bf16 v[10:13], v[138:141], v[230:233], v[10:13]
	s_setprio 0
	s_setprio 1
	v_mfma_f32_16x16x32_bf16 v[62:65], v[134:137], v[196:199], v[62:65]
	v_mfma_f32_16x16x32_bf16 v[58:61], v[142:145], v[196:199], v[58:61]
	v_mfma_f32_16x16x32_bf16 v[46:49], v[134:137], v[204:207], v[46:49]
	v_mfma_f32_16x16x32_bf16 v[42:45], v[142:145], v[204:207], v[42:45]
	v_mfma_f32_16x16x32_bf16 v[30:33], v[134:137], v[226:229], v[30:33]
	v_mfma_f32_16x16x32_bf16 v[26:29], v[142:145], v[226:229], v[26:29]
	v_mfma_f32_16x16x32_bf16 v[14:17], v[134:137], v[234:237], v[14:17]
	v_mfma_f32_16x16x32_bf16 v[10:13], v[142:145], v[234:237], v[10:13]
	s_setprio 0
	s_setprio 1
	v_mfma_f32_16x16x32_bf16 v[54:57], v[176:179], v[192:195], v[54:57]
	v_mfma_f32_16x16x32_bf16 v[50:53], v[184:187], v[192:195], v[50:53]
	v_mfma_f32_16x16x32_bf16 v[38:41], v[176:179], v[200:203], v[38:41]
	v_mfma_f32_16x16x32_bf16 v[34:37], v[184:187], v[200:203], v[34:37]
	v_mfma_f32_16x16x32_bf16 v[22:25], v[176:179], v[222:225], v[22:25]
	v_mfma_f32_16x16x32_bf16 v[18:21], v[184:187], v[222:225], v[18:21]
	v_mfma_f32_16x16x32_bf16 v[6:9], v[176:179], v[230:233], v[6:9]
	v_mfma_f32_16x16x32_bf16 v[2:5], v[184:187], v[230:233], v[2:5]
	s_setprio 0
	s_setprio 1
	v_mfma_f32_16x16x32_bf16 v[54:57], v[180:183], v[196:199], v[54:57]
	v_mfma_f32_16x16x32_bf16 v[50:53], v[188:191], v[196:199], v[50:53]
	v_mfma_f32_16x16x32_bf16 v[38:41], v[180:183], v[204:207], v[38:41]
	v_mfma_f32_16x16x32_bf16 v[34:37], v[188:191], v[204:207], v[34:37]
	v_mfma_f32_16x16x32_bf16 v[22:25], v[180:183], v[226:229], v[22:25]
	v_mfma_f32_16x16x32_bf16 v[18:21], v[188:191], v[226:229], v[18:21]
	v_mfma_f32_16x16x32_bf16 v[6:9], v[180:183], v[234:237], v[6:9]
	v_mfma_f32_16x16x32_bf16 v[2:5], v[188:191], v[234:237], v[2:5]
	s_setprio 0
	s_barrier
	s_add_i32 s85, s85, 2
	s_add_u32 s75, s75, 0x100
	s_addc_u32 s84, s84, 0
	s_cmpk_gt_u32 s85, 0x53
	s_mov_b64 s[44:45], s[62:63]
	s_cbranch_scc0 .LBB0_339
	s_and_b64 vcc, exec, s[50:51]
	s_cbranch_vccz .LBB0_342
	s_barrier
